# in-proj GEMM epilogue: pairs of 8-byte stores merged into 16-byte stores via v_permlane16_swap (both the QKV scatter and the gate-sigmoid paths)
# speedup vs baseline: 1.0038x; 1.0038x over previous
; __device__ __forceinline__ unsigned cvt_pk_bf16(float lo, float hi) { f32x2_c v = {lo, hi}; bf16x2_c b = __builtin_convertvector(v, bf16x2_c); return __builtin_bit_cast(unsigned, b); }
; __device__ __forceinline__ float sigmoidf_(float x) { return __builtin_amdgcn_rcpf(1.0f + __expf(-x)); }
;     __device__ __forceinline__ void operator()(const f32x4 (&acc)[2][2][4][2], const Unit& u, int wr, int wc, int fr, int fq) const {
;     ...
;             const int col0 = (pn - 24) * BM + wc * 32 + 4 * fq;
; #pragma unroll
;             for (int ai = 0; ai < 2; ++ai)
; #pragma unroll
;                 for (int m = 0; m < 4; ++m) { bf16_t* rowp = SG + (size_t)(row0 + ai * HALF + m * 16) * 4096 + col0;
; #pragma unroll
;                     for (int bj = 0; bj < 2; ++bj)
; #pragma unroll
;                         for (int n = 0; n < 2; ++n) { const f32x4 v = acc[ai][bj][m][n]; u32x2 w; w.x = cvt_pk_bf16(sigmoidf_(v[0]), sigmoidf_(v[1])); w.y = cvt_pk_bf16(sigmoidf_(v[2]), sigmoidf_(v[3]));
;                             *(u32x2*)(rowp + bj * HALF + n * 16) = w; } }
.LBB0_211:
	v_ashrrev_i32_e32 v131, 31, v130
	v_lshlrev_b64 v[132:133], 13, v[130:131]
	v_mul_f32_e32 v131, 0xbfb8aa3b, v126
	v_mul_f32_e32 v136, 0xbfb8aa3b, v127
	v_exp_f32_e32 v131, v131
	v_exp_f32_e32 v136, v136
	v_mul_f32_e32 v137, 0xbfb8aa3b, v128
	v_mul_f32_e32 v138, 0xbfb8aa3b, v129
	v_add_f32_e32 v131, 1.0, v131
	v_add_f32_e32 v136, 1.0, v136
	v_rcp_f32_e32 v131, v131
	v_rcp_f32_e32 v136, v136
	v_exp_f32_e32 v137, v137
	v_exp_f32_e32 v138, v138
	v_mul_f32_e32 v139, 0xbfb8aa3b, v123
	v_cvt_pk_bf16_f32 v136, v131, v136
	v_add_f32_e32 v131, 1.0, v137
	v_add_f32_e32 v137, 1.0, v138
	v_mul_f32_e32 v138, 0xbfb8aa3b, v122
	v_exp_f32_e32 v138, v138
	v_exp_f32_e32 v139, v139
	v_mul_f32_e32 v140, 0xbfb8aa3b, v124
	v_mul_f32_e32 v141, 0xbfb8aa3b, v125
	v_rcp_f32_e32 v131, v131
	v_rcp_f32_e32 v137, v137
	v_add_f32_e32 v138, 1.0, v138
	v_add_f32_e32 v139, 1.0, v139
	v_exp_f32_e32 v140, v140
	v_exp_f32_e32 v141, v141
	v_rcp_f32_e32 v138, v138
	v_rcp_f32_e32 v139, v139
	v_lshl_add_u32 v148, s16, 8, v175
	v_lshl_add_u64 v[132:133], s[20:21], 0, v[132:133]
	v_lshlrev_b64 v[134:135], 1, v[148:149]
	v_and_b32_e32 v196, 16, v198
	v_lshrrev_b32_e32 v197, 1, v196
	v_add3_u32 v134, v134, v196, v197
	v_lshl_add_u64 v[132:133], v[132:133], 0, v[134:135]
	v_add_f32_e32 v140, 1.0, v140
	v_add_f32_e32 v141, 1.0, v141
	v_cvt_pk_bf16_f32 v137, v131, v137
	v_rcp_f32_e32 v140, v140
	v_rcp_f32_e32 v141, v141
	v_mov_b32_e32 v188, v136
	v_mov_b32_e32 v189, v137
	v_cvt_pk_bf16_f32 v136, v138, v139
	v_mul_f32_e32 v131, 0xbfb8aa3b, v118
	v_mul_f32_e32 v138, 0xbfb8aa3b, v119
	v_exp_f32_e32 v131, v131
	v_exp_f32_e32 v138, v138
	v_cvt_pk_bf16_f32 v137, v140, v141
	v_mov_b32_e32 v190, v136
	v_mov_b32_e32 v191, v137
	s_nop 1
	v_permlane16_swap_b32_e32 v188, v190
	v_permlane16_swap_b32_e32 v189, v191
	global_store_dwordx4 v[132:133], v[188:191], off
	v_add_f32_e32 v131, 1.0, v131
	v_add_f32_e32 v136, 1.0, v138
	v_mul_f32_e32 v137, 0xbfb8aa3b, v120
	v_mul_f32_e32 v138, 0xbfb8aa3b, v121
	v_rcp_f32_e32 v131, v131
	v_rcp_f32_e32 v136, v136
	v_exp_f32_e32 v137, v137
	v_exp_f32_e32 v138, v138
	v_mul_f32_e32 v139, 0xbfb8aa3b, v115
	v_cvt_pk_bf16_f32 v136, v131, v136
	v_add_f32_e32 v131, 1.0, v137
	v_add_f32_e32 v137, 1.0, v138
	v_mul_f32_e32 v138, 0xbfb8aa3b, v114
	v_exp_f32_e32 v138, v138
	v_exp_f32_e32 v139, v139
	v_rcp_f32_e32 v131, v131
	v_rcp_f32_e32 v137, v137
	v_add_f32_e32 v138, 1.0, v138
	v_add_f32_e32 v139, 1.0, v139
	v_mul_f32_e32 v140, 0xbfb8aa3b, v116
	v_mul_f32_e32 v141, 0xbfb8aa3b, v117
	v_rcp_f32_e32 v138, v138
	v_exp_f32_e32 v140, v140
	v_exp_f32_e32 v141, v141
	v_rcp_f32_e32 v139, v139
	v_cvt_pk_bf16_f32 v137, v131, v137
	v_add_f32_e32 v140, 1.0, v140
	v_add_f32_e32 v141, 1.0, v141
	v_mov_b32_e32 v192, v136
	v_mov_b32_e32 v193, v137
	v_cvt_pk_bf16_f32 v136, v138, v139
	v_mul_f32_e32 v131, 0xbfb8aa3b, v110
	v_mul_f32_e32 v138, 0xbfb8aa3b, v111
	v_rcp_f32_e32 v140, v140
	v_rcp_f32_e32 v141, v141
	v_exp_f32_e32 v131, v131
	v_exp_f32_e32 v138, v138
	v_mul_f32_e32 v139, 0xbfb8aa3b, v112
	v_cvt_pk_bf16_f32 v137, v140, v141
	v_add_f32_e32 v131, 1.0, v131
	v_add_f32_e32 v138, 1.0, v138
	v_mul_f32_e32 v140, 0xbfb8aa3b, v113
	v_rcp_f32_e32 v131, v131
	v_rcp_f32_e32 v138, v138
	v_exp_f32_e32 v139, v139
	v_exp_f32_e32 v140, v140
	v_mul_f32_e32 v141, 0xbfb8aa3b, v107
	v_cvt_pk_bf16_f32 v138, v131, v138
	v_add_f32_e32 v131, 1.0, v139
	v_add_f32_e32 v139, 1.0, v140
	v_mul_f32_e32 v140, 0xbfb8aa3b, v106
	v_exp_f32_e32 v140, v140
	v_exp_f32_e32 v141, v141
	v_mul_f32_e32 v142, 0xbfb8aa3b, v108
	v_mul_f32_e32 v143, 0xbfb8aa3b, v109
	v_mov_b32_e32 v194, v136
	v_mov_b32_e32 v195, v137
	s_nop 1
	v_permlane16_swap_b32_e32 v192, v194
	v_permlane16_swap_b32_e32 v193, v195
	global_store_dwordx4 v[132:133], v[192:195], off offset:256
	v_or_b32_e32 v136, 16, v130
	v_rcp_f32_e32 v131, v131
	v_rcp_f32_e32 v139, v139
	v_add_f32_e32 v140, 1.0, v140
	v_add_f32_e32 v141, 1.0, v141
	v_exp_f32_e32 v142, v142
	v_exp_f32_e32 v143, v143
	v_ashrrev_i32_e32 v137, 31, v136
	v_rcp_f32_e32 v140, v140
	v_rcp_f32_e32 v141, v141
	v_lshlrev_b64 v[136:137], 13, v[136:137]
	v_lshl_add_u64 v[136:137], s[20:21], 0, v[136:137]
	v_lshl_add_u64 v[136:137], v[136:137], 0, v[134:135]
	v_add_f32_e32 v142, 1.0, v142
	v_add_f32_e32 v143, 1.0, v143
	v_cvt_pk_bf16_f32 v139, v131, v139
	v_rcp_f32_e32 v142, v142
	v_rcp_f32_e32 v143, v143
	v_mov_b32_e32 v188, v138
	v_mov_b32_e32 v189, v139
	v_cvt_pk_bf16_f32 v138, v140, v141
	v_mul_f32_e32 v131, 0xbfb8aa3b, v102
	v_mul_f32_e32 v140, 0xbfb8aa3b, v103
	v_exp_f32_e32 v131, v131
	v_exp_f32_e32 v140, v140
	v_cvt_pk_bf16_f32 v139, v142, v143
	v_mov_b32_e32 v190, v138
	v_mov_b32_e32 v191, v139
	s_nop 1
	v_permlane16_swap_b32_e32 v188, v190
	v_permlane16_swap_b32_e32 v189, v191
	global_store_dwordx4 v[136:137], v[188:191], off
	v_add_f32_e32 v131, 1.0, v131
	v_add_f32_e32 v138, 1.0, v140
	v_mul_f32_e32 v139, 0xbfb8aa3b, v104
	v_mul_f32_e32 v140, 0xbfb8aa3b, v105
	v_rcp_f32_e32 v131, v131
	v_rcp_f32_e32 v138, v138
	v_exp_f32_e32 v139, v139
	v_exp_f32_e32 v140, v140
	v_mul_f32_e32 v141, 0xbfb8aa3b, v99
	v_cvt_pk_bf16_f32 v138, v131, v138
	v_add_f32_e32 v131, 1.0, v139
	v_add_f32_e32 v139, 1.0, v140
	v_mul_f32_e32 v140, 0xbfb8aa3b, v98
	v_mul_f32_e32 v142, 0xbfb8aa3b, v100
	v_mul_f32_e32 v143, 0xbfb8aa3b, v101
	v_exp_f32_e32 v140, v140
	v_exp_f32_e32 v141, v141
	v_exp_f32_e32 v142, v142
	v_exp_f32_e32 v143, v143
	v_rcp_f32_e32 v131, v131
	v_rcp_f32_e32 v139, v139
	v_add_f32_e32 v140, 1.0, v140
	v_add_f32_e32 v141, 1.0, v141
	v_add_f32_e32 v142, 1.0, v142
	v_add_f32_e32 v143, 1.0, v143
	v_rcp_f32_e32 v140, v140
	v_rcp_f32_e32 v141, v141
	v_rcp_f32_e32 v142, v142
	v_rcp_f32_e32 v143, v143
; __device__ __forceinline__ unsigned cvt_pk_bf16(float lo, float hi) { f32x2_c v = {lo, hi}; bf16x2_c b = __builtin_convertvector(v, bf16x2_c); return __builtin_bit_cast(unsigned, b); }
; __device__ __forceinline__ float sigmoidf_(float x) { return __builtin_amdgcn_rcpf(1.0f + __expf(-x)); }
;     __device__ __forceinline__ void operator()(const f32x4 (&acc)[2][2][4][2], const Unit& u, int wr, int wc, int fr, int fq) const {
;     ...
;             const int col0 = (pn - 24) * BM + wc * 32 + 4 * fq;
; #pragma unroll
;             for (int ai = 0; ai < 2; ++ai)
; #pragma unroll
;                 for (int m = 0; m < 4; ++m) { bf16_t* rowp = SG + (size_t)(row0 + ai * HALF + m * 16) * 4096 + col0;
; #pragma unroll
;                     for (int bj = 0; bj < 2; ++bj)
; #pragma unroll
;                         for (int n = 0; n < 2; ++n) { const f32x4 v = acc[ai][bj][m][n]; u32x2 w; w.x = cvt_pk_bf16(sigmoidf_(v[0]), sigmoidf_(v[1])); w.y = cvt_pk_bf16(sigmoidf_(v[2]), sigmoidf_(v[3]));
;                             *(u32x2*)(rowp + bj * HALF + n * 16) = w; } }
	v_cvt_pk_bf16_f32 v139, v131, v139
	v_mov_b32_e32 v192, v138
	v_mov_b32_e32 v193, v139
	v_cvt_pk_bf16_f32 v138, v140, v141
	v_cvt_pk_bf16_f32 v139, v142, v143
	v_mov_b32_e32 v194, v138
	v_mov_b32_e32 v195, v139
	s_nop 1
	v_permlane16_swap_b32_e32 v192, v194
	v_permlane16_swap_b32_e32 v193, v195
	global_store_dwordx4 v[136:137], v[192:195], off offset:256
	v_mul_f32_e32 v131, 0xbfb8aa3b, v94
	v_mul_f32_e32 v138, 0xbfb8aa3b, v95
	v_exp_f32_e32 v131, v131
	v_exp_f32_e32 v138, v138
	v_mul_f32_e32 v139, 0xbfb8aa3b, v96
	v_mul_f32_e32 v140, 0xbfb8aa3b, v97
	v_add_f32_e32 v131, 1.0, v131
	v_add_f32_e32 v138, 1.0, v138
	v_rcp_f32_e32 v131, v131
	v_rcp_f32_e32 v138, v138
	v_exp_f32_e32 v139, v139
	v_exp_f32_e32 v140, v140
	v_mul_f32_e32 v141, 0xbfb8aa3b, v91
	v_cvt_pk_bf16_f32 v138, v131, v138
	v_add_f32_e32 v131, 1.0, v139
	v_add_f32_e32 v139, 1.0, v140
	v_mul_f32_e32 v140, 0xbfb8aa3b, v90
	v_exp_f32_e32 v140, v140
	v_exp_f32_e32 v141, v141
	v_mul_f32_e32 v142, 0xbfb8aa3b, v92
	v_mul_f32_e32 v143, 0xbfb8aa3b, v93
	v_or_b32_e32 v136, 32, v130
	v_rcp_f32_e32 v131, v131
	v_rcp_f32_e32 v139, v139
	v_add_f32_e32 v140, 1.0, v140
	v_add_f32_e32 v141, 1.0, v141
	v_exp_f32_e32 v142, v142
	v_exp_f32_e32 v143, v143
	v_ashrrev_i32_e32 v137, 31, v136
	v_rcp_f32_e32 v140, v140
	v_rcp_f32_e32 v141, v141
	v_lshlrev_b64 v[136:137], 13, v[136:137]
	v_lshl_add_u64 v[136:137], s[20:21], 0, v[136:137]
	v_lshl_add_u64 v[136:137], v[136:137], 0, v[134:135]
	v_add_f32_e32 v142, 1.0, v142
	v_add_f32_e32 v143, 1.0, v143
	v_cvt_pk_bf16_f32 v139, v131, v139
	v_rcp_f32_e32 v142, v142
	v_rcp_f32_e32 v143, v143
	v_mov_b32_e32 v188, v138
	v_mov_b32_e32 v189, v139
	v_cvt_pk_bf16_f32 v138, v140, v141
	v_mul_f32_e32 v131, 0xbfb8aa3b, v86
	v_mul_f32_e32 v140, 0xbfb8aa3b, v87
	v_exp_f32_e32 v131, v131
	v_exp_f32_e32 v140, v140
	v_cvt_pk_bf16_f32 v139, v142, v143
	v_mov_b32_e32 v190, v138
	v_mov_b32_e32 v191, v139
	s_nop 1
	v_permlane16_swap_b32_e32 v188, v190
	v_permlane16_swap_b32_e32 v189, v191
	global_store_dwordx4 v[136:137], v[188:191], off
	v_add_f32_e32 v131, 1.0, v131
	v_add_f32_e32 v138, 1.0, v140
	v_mul_f32_e32 v139, 0xbfb8aa3b, v88
	v_mul_f32_e32 v140, 0xbfb8aa3b, v89
	v_rcp_f32_e32 v131, v131
	v_rcp_f32_e32 v138, v138
	v_exp_f32_e32 v139, v139
	v_exp_f32_e32 v140, v140
	v_mul_f32_e32 v141, 0xbfb8aa3b, v83
	v_cvt_pk_bf16_f32 v138, v131, v138
	v_add_f32_e32 v131, 1.0, v139
	v_add_f32_e32 v139, 1.0, v140
	v_mul_f32_e32 v140, 0xbfb8aa3b, v82
	v_mul_f32_e32 v142, 0xbfb8aa3b, v84
	v_mul_f32_e32 v143, 0xbfb8aa3b, v85
	v_exp_f32_e32 v140, v140
	v_exp_f32_e32 v141, v141
	v_exp_f32_e32 v142, v142
	v_exp_f32_e32 v143, v143
	v_rcp_f32_e32 v131, v131
	v_rcp_f32_e32 v139, v139
	v_add_f32_e32 v140, 1.0, v140
	v_add_f32_e32 v141, 1.0, v141
	v_add_f32_e32 v142, 1.0, v142
	v_add_f32_e32 v143, 1.0, v143
	v_rcp_f32_e32 v140, v140
	v_rcp_f32_e32 v141, v141
	v_rcp_f32_e32 v142, v142
	v_rcp_f32_e32 v143, v143
	v_cvt_pk_bf16_f32 v139, v131, v139
	v_mov_b32_e32 v192, v138
	v_mov_b32_e32 v193, v139
	v_cvt_pk_bf16_f32 v138, v140, v141
	v_cvt_pk_bf16_f32 v139, v142, v143
	v_mov_b32_e32 v194, v138
	v_mov_b32_e32 v195, v139
	s_nop 1
	v_permlane16_swap_b32_e32 v192, v194
	v_permlane16_swap_b32_e32 v193, v195
	global_store_dwordx4 v[136:137], v[192:195], off offset:256
	v_mul_f32_e32 v131, 0xbfb8aa3b, v78
	v_mul_f32_e32 v138, 0xbfb8aa3b, v79
	v_or_b32_e32 v136, 48, v130
	v_exp_f32_e32 v131, v131
	v_exp_f32_e32 v138, v138
	v_ashrrev_i32_e32 v137, 31, v136
	v_lshlrev_b64 v[136:137], 13, v[136:137]
	v_lshl_add_u64 v[136:137], s[20:21], 0, v[136:137]
	v_lshl_add_u64 v[134:135], v[136:137], 0, v[134:135]
	v_add_f32_e32 v131, 1.0, v131
	v_add_f32_e32 v136, 1.0, v138
	v_mul_f32_e32 v137, 0xbfb8aa3b, v80
	v_mul_f32_e32 v138, 0xbfb8aa3b, v81
	v_rcp_f32_e32 v131, v131
	v_rcp_f32_e32 v136, v136
	v_exp_f32_e32 v137, v137
	v_exp_f32_e32 v138, v138
	v_mul_f32_e32 v139, 0xbfb8aa3b, v75
	v_cvt_pk_bf16_f32 v136, v131, v136
	v_add_f32_e32 v131, 1.0, v137
	v_add_f32_e32 v137, 1.0, v138
	v_mul_f32_e32 v138, 0xbfb8aa3b, v74
	v_exp_f32_e32 v138, v138
	v_exp_f32_e32 v139, v139
	v_mul_f32_e32 v140, 0xbfb8aa3b, v76
	v_mul_f32_e32 v141, 0xbfb8aa3b, v77
	v_rcp_f32_e32 v131, v131
	v_rcp_f32_e32 v137, v137
	v_add_f32_e32 v138, 1.0, v138
	v_add_f32_e32 v139, 1.0, v139
	v_exp_f32_e32 v140, v140
	v_exp_f32_e32 v141, v141
	v_rcp_f32_e32 v138, v138
	v_rcp_f32_e32 v139, v139
	v_add_f32_e32 v140, 1.0, v140
	v_add_f32_e32 v141, 1.0, v141
	v_cvt_pk_bf16_f32 v137, v131, v137
	v_rcp_f32_e32 v140, v140
	v_rcp_f32_e32 v141, v141
	v_mov_b32_e32 v188, v136
	v_mov_b32_e32 v189, v137
	v_cvt_pk_bf16_f32 v136, v138, v139
	v_mul_f32_e32 v131, 0xbfb8aa3b, v70
	v_mul_f32_e32 v138, 0xbfb8aa3b, v71
	v_exp_f32_e32 v131, v131
	v_exp_f32_e32 v138, v138
	v_cvt_pk_bf16_f32 v137, v140, v141
	v_mov_b32_e32 v190, v136
	v_mov_b32_e32 v191, v137
	s_nop 1
	v_permlane16_swap_b32_e32 v188, v190
	v_permlane16_swap_b32_e32 v189, v191
	global_store_dwordx4 v[134:135], v[188:191], off
	v_add_f32_e32 v131, 1.0, v131
	v_add_f32_e32 v136, 1.0, v138
	v_mul_f32_e32 v137, 0xbfb8aa3b, v72
	v_mul_f32_e32 v138, 0xbfb8aa3b, v73
	v_rcp_f32_e32 v131, v131
	v_rcp_f32_e32 v136, v136
	v_exp_f32_e32 v137, v137
	v_exp_f32_e32 v138, v138
	v_mul_f32_e32 v139, 0xbfb8aa3b, v67
	v_cvt_pk_bf16_f32 v136, v131, v136
	v_add_f32_e32 v131, 1.0, v137
	v_add_f32_e32 v137, 1.0, v138
	v_mul_f32_e32 v138, 0xbfb8aa3b, v66
	v_mul_f32_e32 v140, 0xbfb8aa3b, v68
	v_mul_f32_e32 v141, 0xbfb8aa3b, v69
	v_exp_f32_e32 v138, v138
	v_exp_f32_e32 v139, v139
	v_exp_f32_e32 v140, v140
	v_exp_f32_e32 v141, v141
	v_rcp_f32_e32 v131, v131
	v_rcp_f32_e32 v137, v137
	v_add_f32_e32 v138, 1.0, v138
	v_add_f32_e32 v139, 1.0, v139
; __device__ __forceinline__ unsigned cvt_pk_bf16(float lo, float hi) { f32x2_c v = {lo, hi}; bf16x2_c b = __builtin_convertvector(v, bf16x2_c); return __builtin_bit_cast(unsigned, b); }
; __device__ __forceinline__ float sigmoidf_(float x) { return __builtin_amdgcn_rcpf(1.0f + __expf(-x)); }
;     __device__ __forceinline__ void operator()(const f32x4 (&acc)[2][2][4][2], const Unit& u, int wr, int wc, int fr, int fq) const {
;     ...
;             const int col0 = (pn - 24) * BM + wc * 32 + 4 * fq;
; #pragma unroll
;             for (int ai = 0; ai < 2; ++ai)
; #pragma unroll
;                 for (int m = 0; m < 4; ++m) { bf16_t* rowp = SG + (size_t)(row0 + ai * HALF + m * 16) * 4096 + col0;
; #pragma unroll
;                     for (int bj = 0; bj < 2; ++bj)
; #pragma unroll
;                         for (int n = 0; n < 2; ++n) { const f32x4 v = acc[ai][bj][m][n]; u32x2 w; w.x = cvt_pk_bf16(sigmoidf_(v[0]), sigmoidf_(v[1])); w.y = cvt_pk_bf16(sigmoidf_(v[2]), sigmoidf_(v[3]));
;                             *(u32x2*)(rowp + bj * HALF + n * 16) = w; } }
	v_add_f32_e32 v140, 1.0, v140
	v_add_f32_e32 v141, 1.0, v141
	v_rcp_f32_e32 v138, v138
	v_rcp_f32_e32 v139, v139
	v_rcp_f32_e32 v140, v140
	v_rcp_f32_e32 v141, v141
	v_cvt_pk_bf16_f32 v137, v131, v137
	v_mov_b32_e32 v192, v136
	v_mov_b32_e32 v193, v137
	v_cvt_pk_bf16_f32 v136, v138, v139
	v_cvt_pk_bf16_f32 v137, v140, v141
	v_mov_b32_e32 v194, v136
	v_mov_b32_e32 v195, v137
	s_nop 1
	v_permlane16_swap_b32_e32 v192, v194
	v_permlane16_swap_b32_e32 v193, v195
	global_store_dwordx4 v[134:135], v[192:195], off offset:256
	v_mul_f32_e32 v131, 0xbfb8aa3b, v62
	v_mul_f32_e32 v134, 0xbfb8aa3b, v63
	v_exp_f32_e32 v131, v131
	v_exp_f32_e32 v136, v134
	v_mul_f32_e32 v137, 0xbfb8aa3b, v64
	v_mul_f32_e32 v138, 0xbfb8aa3b, v65
	v_add_f32_e32 v131, 1.0, v131
	v_add_f32_e32 v136, 1.0, v136
	v_rcp_f32_e32 v131, v131
	v_rcp_f32_e32 v136, v136
	v_exp_f32_e32 v137, v137
	v_exp_f32_e32 v138, v138
	v_mul_f32_e32 v139, 0xbfb8aa3b, v59
	v_cvt_pk_bf16_f32 v136, v131, v136
	v_add_f32_e32 v131, 1.0, v137
	v_add_f32_e32 v137, 1.0, v138
	v_mul_f32_e32 v138, 0xbfb8aa3b, v58
	v_rcp_f32_e32 v131, v131
	v_rcp_f32_e32 v137, v137
	v_exp_f32_e32 v138, v138
	v_exp_f32_e32 v139, v139
	v_mul_f32_e32 v140, 0xbfb8aa3b, v61
	v_cvt_pk_bf16_f32 v137, v131, v137
	v_add_f32_e32 v131, 1.0, v138
	v_add_f32_e32 v138, 1.0, v139
	v_mul_f32_e32 v139, 0xbfb8aa3b, v60
	v_exp_f32_e32 v139, v139
	v_exp_f32_e32 v140, v140
	v_rcp_f32_e32 v131, v131
	v_rcp_f32_e32 v141, v138
	v_add_f32_e32 v138, 1.0, v139
	v_rcp_f32_e32 v142, v138
	v_add_f32_e32 v138, 1.0, v140
	s_mov_b32 s4, 0x100000
	v_rcp_f32_e32 v140, v138
	v_add_co_u32_e32 v138, vcc, s4, v132
	v_lshl_add_u64 v[134:135], v[132:133], 0, s[48:49]
	s_nop 0
	v_addc_co_u32_e32 v139, vcc, 0, v133, vcc
	v_mov_b32_e32 v188, v136
	v_mov_b32_e32 v189, v137
	v_cvt_pk_bf16_f32 v136, v131, v141
	v_mul_f32_e32 v131, 0xbfb8aa3b, v54
	v_mul_f32_e32 v138, 0xbfb8aa3b, v55
	v_exp_f32_e32 v131, v131
	v_exp_f32_e32 v138, v138
	v_cvt_pk_bf16_f32 v137, v142, v140
	v_mov_b32_e32 v190, v136
	v_mov_b32_e32 v191, v137
	s_nop 1
	v_permlane16_swap_b32_e32 v188, v190
	v_permlane16_swap_b32_e32 v189, v191
	global_store_dwordx4 v[134:135], v[188:191], off
	v_add_f32_e32 v131, 1.0, v131
	v_add_f32_e32 v136, 1.0, v138
	v_mul_f32_e32 v137, 0xbfb8aa3b, v56
	v_mul_f32_e32 v138, 0xbfb8aa3b, v57
	v_rcp_f32_e32 v131, v131
	v_rcp_f32_e32 v136, v136
	v_exp_f32_e32 v137, v137
	v_exp_f32_e32 v138, v138
	v_mul_f32_e32 v139, 0xbfb8aa3b, v51
	v_cvt_pk_bf16_f32 v136, v131, v136
	v_add_f32_e32 v131, 1.0, v137
	v_add_f32_e32 v137, 1.0, v138
	v_mul_f32_e32 v138, 0xbfb8aa3b, v50
	v_mul_f32_e32 v140, 0xbfb8aa3b, v52
	v_mul_f32_e32 v141, 0xbfb8aa3b, v53
	v_exp_f32_e32 v138, v138
	v_exp_f32_e32 v139, v139
	v_exp_f32_e32 v140, v140
	v_exp_f32_e32 v141, v141
	v_rcp_f32_e32 v131, v131
	v_rcp_f32_e32 v137, v137
	v_add_f32_e32 v138, 1.0, v138
	v_add_f32_e32 v139, 1.0, v139
	v_add_f32_e32 v140, 1.0, v140
	v_add_f32_e32 v141, 1.0, v141
	v_rcp_f32_e32 v138, v138
	v_rcp_f32_e32 v139, v139
	v_rcp_f32_e32 v140, v140
	v_rcp_f32_e32 v141, v141
	v_cvt_pk_bf16_f32 v137, v131, v137
	v_mov_b32_e32 v192, v136
	v_mov_b32_e32 v193, v137
	v_cvt_pk_bf16_f32 v136, v138, v139
	v_cvt_pk_bf16_f32 v137, v140, v141
	v_mov_b32_e32 v194, v136
	v_mov_b32_e32 v195, v137
	s_nop 1
	v_permlane16_swap_b32_e32 v192, v194
	v_permlane16_swap_b32_e32 v193, v195
	global_store_dwordx4 v[134:135], v[192:195], off offset:256
	v_mul_f32_e32 v131, 0xbfb8aa3b, v46
	v_mul_f32_e32 v134, 0xbfb8aa3b, v47
	v_exp_f32_e32 v131, v131
	v_exp_f32_e32 v136, v134
	v_mul_f32_e32 v137, 0xbfb8aa3b, v48
	v_mul_f32_e32 v138, 0xbfb8aa3b, v49
	v_add_f32_e32 v131, 1.0, v131
	v_add_f32_e32 v136, 1.0, v136
	v_rcp_f32_e32 v131, v131
	v_rcp_f32_e32 v136, v136
	v_exp_f32_e32 v137, v137
	v_exp_f32_e32 v138, v138
	v_mul_f32_e32 v139, 0xbfb8aa3b, v43
	v_cvt_pk_bf16_f32 v136, v131, v136
	v_add_f32_e32 v131, 1.0, v137
	v_add_f32_e32 v137, 1.0, v138
	v_mul_f32_e32 v138, 0xbfb8aa3b, v42
	v_rcp_f32_e32 v131, v131
	v_rcp_f32_e32 v137, v137
	v_exp_f32_e32 v138, v138
	v_exp_f32_e32 v139, v139
	v_mul_f32_e32 v140, 0xbfb8aa3b, v45
	v_cvt_pk_bf16_f32 v137, v131, v137
	v_add_f32_e32 v131, 1.0, v138
	v_add_f32_e32 v138, 1.0, v139
	v_mul_f32_e32 v139, 0xbfb8aa3b, v44
	v_exp_f32_e32 v139, v139
	v_exp_f32_e32 v140, v140
	s_mov_b64 s[4:5], 0x120000
	v_rcp_f32_e32 v131, v131
	v_rcp_f32_e32 v141, v138
	v_add_f32_e32 v138, 1.0, v139
	v_lshl_add_u64 v[134:135], v[132:133], 0, s[4:5]
	v_rcp_f32_e32 v142, v138
	v_add_f32_e32 v138, 1.0, v140
	s_mov_b32 s4, 0x120000
	v_rcp_f32_e32 v140, v138
	v_add_co_u32_e32 v138, vcc, s4, v132
	s_mov_b64 s[4:5], 0x140000
	s_nop 0
	v_addc_co_u32_e32 v139, vcc, 0, v133, vcc
	v_mov_b32_e32 v188, v136
	v_mov_b32_e32 v189, v137
	v_cvt_pk_bf16_f32 v136, v131, v141
	v_mul_f32_e32 v131, 0xbfb8aa3b, v38
	v_mul_f32_e32 v138, 0xbfb8aa3b, v39
	v_exp_f32_e32 v131, v131
	v_exp_f32_e32 v138, v138
	v_cvt_pk_bf16_f32 v137, v142, v140
	v_mov_b32_e32 v190, v136
	v_mov_b32_e32 v191, v137
	s_nop 1
	v_permlane16_swap_b32_e32 v188, v190
	v_permlane16_swap_b32_e32 v189, v191
	global_store_dwordx4 v[134:135], v[188:191], off
	v_add_f32_e32 v131, 1.0, v131
	v_add_f32_e32 v136, 1.0, v138
	v_mul_f32_e32 v137, 0xbfb8aa3b, v40
	v_mul_f32_e32 v138, 0xbfb8aa3b, v41
	v_rcp_f32_e32 v131, v131
	v_rcp_f32_e32 v136, v136
	v_exp_f32_e32 v137, v137
	v_exp_f32_e32 v138, v138
	v_mul_f32_e32 v139, 0xbfb8aa3b, v35
	v_cvt_pk_bf16_f32 v136, v131, v136
	v_add_f32_e32 v131, 1.0, v137
	v_add_f32_e32 v137, 1.0, v138
	v_mul_f32_e32 v138, 0xbfb8aa3b, v34
	v_mul_f32_e32 v140, 0xbfb8aa3b, v36
	v_mul_f32_e32 v141, 0xbfb8aa3b, v37
	v_exp_f32_e32 v138, v138
	v_exp_f32_e32 v139, v139
	v_exp_f32_e32 v140, v140
; __device__ __forceinline__ unsigned cvt_pk_bf16(float lo, float hi) { f32x2_c v = {lo, hi}; bf16x2_c b = __builtin_convertvector(v, bf16x2_c); return __builtin_bit_cast(unsigned, b); }
; __device__ __forceinline__ float sigmoidf_(float x) { return __builtin_amdgcn_rcpf(1.0f + __expf(-x)); }
;     __device__ __forceinline__ void operator()(const f32x4 (&acc)[2][2][4][2], const Unit& u, int wr, int wc, int fr, int fq) const {
;     ...
;             const int col0 = (pn - 24) * BM + wc * 32 + 4 * fq;
; #pragma unroll
;             for (int ai = 0; ai < 2; ++ai)
; #pragma unroll
;                 for (int m = 0; m < 4; ++m) { bf16_t* rowp = SG + (size_t)(row0 + ai * HALF + m * 16) * 4096 + col0;
; #pragma unroll
;                     for (int bj = 0; bj < 2; ++bj)
; #pragma unroll
;                         for (int n = 0; n < 2; ++n) { const f32x4 v = acc[ai][bj][m][n]; u32x2 w; w.x = cvt_pk_bf16(sigmoidf_(v[0]), sigmoidf_(v[1])); w.y = cvt_pk_bf16(sigmoidf_(v[2]), sigmoidf_(v[3]));
;                             *(u32x2*)(rowp + bj * HALF + n * 16) = w; } }
	v_exp_f32_e32 v141, v141
	v_rcp_f32_e32 v131, v131
	v_rcp_f32_e32 v137, v137
	v_add_f32_e32 v138, 1.0, v138
	v_add_f32_e32 v139, 1.0, v139
	v_add_f32_e32 v140, 1.0, v140
	v_add_f32_e32 v141, 1.0, v141
	v_rcp_f32_e32 v138, v138
	v_rcp_f32_e32 v139, v139
	v_rcp_f32_e32 v140, v140
	v_rcp_f32_e32 v141, v141
	v_cvt_pk_bf16_f32 v137, v131, v137
	v_mov_b32_e32 v192, v136
	v_mov_b32_e32 v193, v137
	v_cvt_pk_bf16_f32 v136, v138, v139
	v_cvt_pk_bf16_f32 v137, v140, v141
	v_mov_b32_e32 v194, v136
	v_mov_b32_e32 v195, v137
	s_nop 1
	v_permlane16_swap_b32_e32 v192, v194
	v_permlane16_swap_b32_e32 v193, v195
	global_store_dwordx4 v[134:135], v[192:195], off offset:256
	v_mul_f32_e32 v131, 0xbfb8aa3b, v30
	v_mul_f32_e32 v134, 0xbfb8aa3b, v31
	v_exp_f32_e32 v131, v131
	v_exp_f32_e32 v136, v134
	v_mul_f32_e32 v137, 0xbfb8aa3b, v32
	v_mul_f32_e32 v138, 0xbfb8aa3b, v33
	v_add_f32_e32 v131, 1.0, v131
	v_add_f32_e32 v136, 1.0, v136
	v_rcp_f32_e32 v131, v131
	v_rcp_f32_e32 v136, v136
	v_exp_f32_e32 v137, v137
	v_exp_f32_e32 v138, v138
	v_mul_f32_e32 v139, 0xbfb8aa3b, v27
	v_cvt_pk_bf16_f32 v136, v131, v136
	v_add_f32_e32 v131, 1.0, v137
	v_add_f32_e32 v137, 1.0, v138
	v_mul_f32_e32 v138, 0xbfb8aa3b, v26
	v_rcp_f32_e32 v131, v131
	v_rcp_f32_e32 v137, v137
	v_exp_f32_e32 v138, v138
	v_exp_f32_e32 v139, v139
	v_mul_f32_e32 v140, 0xbfb8aa3b, v29
	v_cvt_pk_bf16_f32 v137, v131, v137
	v_add_f32_e32 v131, 1.0, v138
	v_add_f32_e32 v138, 1.0, v139
	v_mul_f32_e32 v139, 0xbfb8aa3b, v28
	v_exp_f32_e32 v139, v139
	v_exp_f32_e32 v140, v140
	v_rcp_f32_e32 v131, v131
	v_rcp_f32_e32 v141, v138
	v_add_f32_e32 v138, 1.0, v139
	v_lshl_add_u64 v[134:135], v[132:133], 0, s[4:5]
	v_rcp_f32_e32 v142, v138
	v_add_f32_e32 v138, 1.0, v140
	s_mov_b32 s4, 0x140000
	v_rcp_f32_e32 v140, v138
	v_add_co_u32_e32 v138, vcc, s4, v132
	s_mov_b64 s[4:5], 0x160000
	s_nop 0
	v_addc_co_u32_e32 v139, vcc, 0, v133, vcc
	v_mov_b32_e32 v188, v136
	v_mov_b32_e32 v189, v137
	v_cvt_pk_bf16_f32 v136, v131, v141
	v_mul_f32_e32 v131, 0xbfb8aa3b, v22
	v_mul_f32_e32 v138, 0xbfb8aa3b, v23
	v_exp_f32_e32 v131, v131
	v_exp_f32_e32 v138, v138
	v_cvt_pk_bf16_f32 v137, v142, v140
	v_mov_b32_e32 v190, v136
	v_mov_b32_e32 v191, v137
	s_nop 1
	v_permlane16_swap_b32_e32 v188, v190
	v_permlane16_swap_b32_e32 v189, v191
	global_store_dwordx4 v[134:135], v[188:191], off
	v_add_f32_e32 v131, 1.0, v131
	v_add_f32_e32 v136, 1.0, v138
	v_mul_f32_e32 v137, 0xbfb8aa3b, v24
	v_mul_f32_e32 v138, 0xbfb8aa3b, v25
	v_rcp_f32_e32 v131, v131
	v_rcp_f32_e32 v136, v136
	v_exp_f32_e32 v137, v137
	v_exp_f32_e32 v138, v138
	v_mul_f32_e32 v139, 0xbfb8aa3b, v19
	v_cvt_pk_bf16_f32 v136, v131, v136
	v_add_f32_e32 v131, 1.0, v137
	v_add_f32_e32 v137, 1.0, v138
	v_mul_f32_e32 v138, 0xbfb8aa3b, v18
	v_mul_f32_e32 v140, 0xbfb8aa3b, v20
	v_mul_f32_e32 v141, 0xbfb8aa3b, v21
	v_exp_f32_e32 v138, v138
	v_exp_f32_e32 v139, v139
	v_exp_f32_e32 v140, v140
	v_exp_f32_e32 v141, v141
	v_rcp_f32_e32 v131, v131
	v_rcp_f32_e32 v137, v137
	v_add_f32_e32 v138, 1.0, v138
	v_add_f32_e32 v139, 1.0, v139
	v_add_f32_e32 v140, 1.0, v140
	v_add_f32_e32 v141, 1.0, v141
	v_rcp_f32_e32 v138, v138
	v_rcp_f32_e32 v139, v139
	v_rcp_f32_e32 v140, v140
	v_rcp_f32_e32 v141, v141
	v_cvt_pk_bf16_f32 v137, v131, v137
	v_mov_b32_e32 v192, v136
	v_mov_b32_e32 v193, v137
	v_cvt_pk_bf16_f32 v136, v138, v139
	v_cvt_pk_bf16_f32 v137, v140, v141
	v_mov_b32_e32 v194, v136
	v_mov_b32_e32 v195, v137
	s_nop 1
	v_permlane16_swap_b32_e32 v192, v194
	v_permlane16_swap_b32_e32 v193, v195
	global_store_dwordx4 v[134:135], v[192:195], off offset:256
	v_mul_f32_e32 v131, 0xbfb8aa3b, v14
	v_mul_f32_e32 v134, 0xbfb8aa3b, v15
	v_exp_f32_e32 v131, v131
	v_exp_f32_e32 v136, v134
	v_mul_f32_e32 v137, 0xbfb8aa3b, v16
	v_mul_f32_e32 v138, 0xbfb8aa3b, v17
	v_add_f32_e32 v131, 1.0, v131
	v_add_f32_e32 v136, 1.0, v136
	v_rcp_f32_e32 v131, v131
	v_rcp_f32_e32 v136, v136
	v_exp_f32_e32 v137, v137
	v_exp_f32_e32 v138, v138
	v_mul_f32_e32 v139, 0xbfb8aa3b, v11
	v_cvt_pk_bf16_f32 v136, v131, v136
	v_add_f32_e32 v131, 1.0, v137
	v_add_f32_e32 v137, 1.0, v138
	v_mul_f32_e32 v138, 0xbfb8aa3b, v10
	v_rcp_f32_e32 v131, v131
	v_rcp_f32_e32 v137, v137
	v_exp_f32_e32 v138, v138
	v_exp_f32_e32 v139, v139
	v_mul_f32_e32 v140, 0xbfb8aa3b, v13
	v_cvt_pk_bf16_f32 v137, v131, v137
	v_add_f32_e32 v131, 1.0, v138
	v_add_f32_e32 v138, 1.0, v139
	v_mul_f32_e32 v139, 0xbfb8aa3b, v12
	v_exp_f32_e32 v139, v139
	v_exp_f32_e32 v140, v140
	v_rcp_f32_e32 v131, v131
	v_rcp_f32_e32 v138, v138
	v_lshl_add_u64 v[134:135], v[132:133], 0, s[4:5]
	s_mov_b32 s4, 0x160000
	v_add_co_u32_e32 v132, vcc, s4, v132
	v_add_f32_e32 v139, 1.0, v139
	v_add_f32_e32 v140, 1.0, v140
	v_addc_co_u32_e32 v133, vcc, 0, v133, vcc
	v_rcp_f32_e32 v139, v139
	v_rcp_f32_e32 v140, v140
	v_mov_b32_e32 v188, v136
	v_mov_b32_e32 v189, v137
	v_cvt_pk_bf16_f32 v132, v131, v138
	v_mul_f32_e32 v131, 0xbfb8aa3b, v6
	v_mul_f32_e32 v136, 0xbfb8aa3b, v7
	v_exp_f32_e32 v131, v131
	v_exp_f32_e32 v136, v136
	v_cvt_pk_bf16_f32 v133, v139, v140
	v_mov_b32_e32 v190, v132
	v_mov_b32_e32 v191, v133
	s_nop 1
	v_permlane16_swap_b32_e32 v188, v190
	v_permlane16_swap_b32_e32 v189, v191
	global_store_dwordx4 v[134:135], v[188:191], off
	v_add_f32_e32 v131, 1.0, v131
	v_add_f32_e32 v132, 1.0, v136
	v_mul_f32_e32 v133, 0xbfb8aa3b, v8
	v_mul_f32_e32 v136, 0xbfb8aa3b, v9
	v_rcp_f32_e32 v131, v131
	v_rcp_f32_e32 v132, v132
	v_exp_f32_e32 v133, v133
	v_exp_f32_e32 v136, v136
	v_mul_f32_e32 v137, 0xbfb8aa3b, v3
	v_cvt_pk_bf16_f32 v132, v131, v132
	v_add_f32_e32 v131, 1.0, v133
	v_add_f32_e32 v133, 1.0, v136
	v_mul_f32_e32 v136, 0xbfb8aa3b, v2
	v_mul_f32_e32 v138, 0xbfb8aa3b, v4
	v_mul_f32_e32 v139, 0xbfb8aa3b, v5
	v_exp_f32_e32 v136, v136
	v_exp_f32_e32 v137, v137
	v_exp_f32_e32 v138, v138
	v_exp_f32_e32 v139, v139
	v_rcp_f32_e32 v131, v131
	v_rcp_f32_e32 v133, v133
	v_add_f32_e32 v136, 1.0, v136
	v_add_f32_e32 v137, 1.0, v137
	v_add_f32_e32 v138, 1.0, v138
	v_add_f32_e32 v139, 1.0, v139
	v_rcp_f32_e32 v136, v136
	v_rcp_f32_e32 v137, v137
	v_rcp_f32_e32 v138, v138
	v_rcp_f32_e32 v139, v139
	v_cvt_pk_bf16_f32 v133, v131, v133
	v_mov_b32_e32 v192, v132
	v_mov_b32_e32 v193, v133
	v_cvt_pk_bf16_f32 v132, v136, v137
	v_cvt_pk_bf16_f32 v133, v138, v139
	v_mov_b32_e32 v194, v132
	v_mov_b32_e32 v195, v133
	s_nop 1
	v_permlane16_swap_b32_e32 v192, v194
	v_permlane16_swap_b32_e32 v193, v195
	global_store_dwordx4 v[134:135], v[192:195], off offset:256
	s_cbranch_execnz .LBB0_265

; __device__ __forceinline__ unsigned cvt_pk_bf16(float lo, float hi) { f32x2_c v = {lo, hi}; bf16x2_c b = __builtin_convertvector(v, bf16x2_c); return __builtin_bit_cast(unsigned, b); }
;     __device__ __forceinline__ void operator()(const f32x4 (&acc)[2][2][4][2], const Unit& u, int wr, int wc, int fr, int fq) const {
;     ...
;         if (pn < 24) {
;             const int sec = pn >> 2; const bool rot = (sec != 2) && (sec != 5) && (wc == 0);
;             const int b = (u.pm * BM) / SEQ;
;             f32x4 ks[2][2] = {{(f32x4){0.f, 0.f, 0.f, 0.f}, (f32x4){0.f, 0.f, 0.f, 0.f}}, {(f32x4){0.f, 0.f, 0.f, 0.f}, (f32x4){0.f, 0.f, 0.f, 0.f}}};
; #pragma unroll
;             for (int ai = 0; ai < 2; ++ai)
; #pragma unroll
;                 for (int m = 0; m < 4; ++m) { const int r = row0 + ai * HALF + m * 16, pos = r - b * SEQ;
;                     f32x4 cs = (f32x4){1.f, 1.f, 1.f, 1.f}, sn = (f32x4){0.f, 0.f, 0.f, 0.f};
;                     if (rot) { cs = *(const f32x4*)(rope + (size_t)pos * 32 + 4 * fq); sn = *(const f32x4*)(rope + (size_t)pos * 32 + 16 + 4 * fq); }
; #pragma unroll
;                     for (int bj = 0; bj < 2; ++bj) { const int h8 = (pn & 3) * 2 + bj; f32x4 v0 = acc[ai][bj][m][0], v1 = acc[ai][bj][m][1];
;                         if (rot) { const f32x4 a = v0 * cs - v1 * sn, bb = v1 * cs + v0 * sn; v0 = a; v1 = bb; }
;                         if (sec == 1) { ks[bj][0] += v0; ks[bj][1] += v1; }
;                         bf16_t* dst = QKV + (size_t)sec * SEC_ELEMS + ((size_t)(b * NH8 + h8) * SEQ + pos) * 128 + wc * 32 + 4 * fq;
;                         u32x2 w0, w1; w0.x = cvt_pk_bf16(v0[0], v0[1]); w0.y = cvt_pk_bf16(v0[2], v0[3]); w1.x = cvt_pk_bf16(v1[0], v1[1]); w1.y = cvt_pk_bf16(v1[2], v1[3]);
;                         *(u32x2*)dst = w0; *(u32x2*)(dst + 16) = w1; } }
.LBB0_217:
	s_lshl_b32 s15, s16, 1
	s_and_b32 s15, s15, 6
	s_ashr_i32 s79, s78, 31
	s_lshl_b32 s16, s14, 3
	s_lshl_b64 s[24:25], s[78:79], 26
	s_or_b32 s74, s16, s15
	s_add_u32 s15, s91, s24
	s_addc_u32 s26, s92, s25
	s_ashr_i32 s75, s74, 31
	s_waitcnt vmcnt(0)
	v_pk_mul_f32 v[166:167], v[122:123], v[136:137]
	s_lshl_b64 s[24:25], s[74:75], 22
	v_pk_fma_f32 v[168:169], v[126:127], v[140:141], v[166:167] neg_lo:[0,0,1] neg_hi:[0,0,1]
	v_pk_mul_f32 v[166:167], v[122:123], v[140:141]
	s_add_u32 s80, s15, s24
	v_lshlrev_b64 v[132:133], 8, v[170:171]
	v_pk_mul_f32 v[164:165], v[124:125], v[138:139]
	v_pk_fma_f32 v[166:167], v[126:127], v[136:137], v[166:167]
	s_addc_u32 s81, s26, s25
	v_pk_fma_f32 v[172:173], v[128:129], v[142:143], v[164:165] neg_lo:[0,0,1] neg_hi:[0,0,1]
	v_pk_mul_f32 v[164:165], v[124:125], v[142:143]
	v_cndmask_b32_e64 v167, v123, v167, s[76:77]
	v_cndmask_b32_e64 v166, v122, v166, s[76:77]
	v_lshl_add_u64 v[122:123], s[80:81], 0, v[132:133]
	s_lshl_b32 s16, s93, 1
	s_or_b32 s72, s74, 1
	v_pk_fma_f32 v[164:165], v[128:129], v[138:139], v[164:165]
	v_cndmask_b32_e64 v169, v127, v169, s[76:77]
	v_cndmask_b32_e64 v168, v126, v168, s[76:77]
	v_cndmask_b32_e64 v129, v129, v173, s[76:77]
	v_cndmask_b32_e64 v128, v128, v172, s[76:77]
	v_lshl_add_u64 v[122:123], v[122:123], 0, s[16:17]
	v_lshlrev_b32_e32 v148, 1, v150
	v_and_b32_e32 v196, 16, v198
	v_lshrrev_b32_e32 v197, 1, v196
	v_add3_u32 v148, v148, v196, v197
	s_ashr_i32 s73, s72, 31
	v_cndmask_b32_e64 v165, v125, v165, s[76:77]
	v_cndmask_b32_e64 v164, v124, v164, s[76:77]
	v_lshl_add_u64 v[122:123], v[122:123], 0, v[148:149]
	v_cvt_pk_bf16_f32 v124, v168, v169
	v_cvt_pk_bf16_f32 v125, v128, v129
	s_lshl_b64 s[24:25], s[72:73], 22
	v_cvt_pk_bf16_f32 v126, v166, v167
	v_cvt_pk_bf16_f32 v127, v164, v165
	s_nop 1
	v_permlane16_swap_b32_e32 v124, v126
	v_permlane16_swap_b32_e32 v125, v127
	global_store_dwordx4 v[122:123], v[124:127], off
	s_nop 1
	v_pk_mul_f32 v[122:123], v[116:117], v[138:139]
	v_pk_mul_f32 v[124:125], v[114:115], v[136:137]
	s_add_u32 s82, s15, s24
	v_pk_fma_f32 v[126:127], v[120:121], v[142:143], v[122:123] neg_lo:[0,0,1] neg_hi:[0,0,1]
	v_pk_fma_f32 v[124:125], v[118:119], v[140:141], v[124:125] neg_lo:[0,0,1] neg_hi:[0,0,1]
	v_pk_mul_f32 v[122:123], v[116:117], v[142:143]
	v_pk_mul_f32 v[140:141], v[114:115], v[140:141]
	s_addc_u32 s83, s26, s25
	v_pk_fma_f32 v[138:139], v[120:121], v[138:139], v[122:123]
	v_pk_fma_f32 v[122:123], v[118:119], v[136:137], v[140:141]
	v_cndmask_b32_e64 v125, v119, v125, s[76:77]
	v_cndmask_b32_e64 v124, v118, v124, s[76:77]
	v_lshl_add_u64 v[118:119], s[82:83], 0, v[132:133]
	v_cndmask_b32_e64 v123, v115, v123, s[76:77]
	v_cndmask_b32_e64 v122, v114, v122, s[76:77]
	v_cndmask_b32_e64 v115, v117, v139, s[76:77]
	v_cndmask_b32_e64 v114, v116, v138, s[76:77]
	v_cndmask_b32_e64 v117, v121, v127, s[76:77]
	v_cndmask_b32_e64 v116, v120, v126, s[76:77]
	v_lshl_add_u64 v[118:119], v[118:119], 0, s[16:17]
	v_lshl_add_u64 v[118:119], v[118:119], 0, v[148:149]
	v_cvt_pk_bf16_f32 v120, v124, v125
	v_cvt_pk_bf16_f32 v121, v116, v117
	v_cvt_pk_bf16_f32 v126, v122, v123
	v_cvt_pk_bf16_f32 v127, v114, v115
	s_nop 1
	v_permlane16_swap_b32_e32 v120, v126
	v_permlane16_swap_b32_e32 v121, v127
	v_mov_b32_e32 v188, v120
	v_mov_b32_e32 v189, v121
	v_mov_b32_e32 v190, v126
	v_mov_b32_e32 v191, v127
	global_store_dwordx4 v[118:119], v[188:191], off
	v_or_b32_e32 v118, 16, v170
	v_ashrrev_i32_e32 v119, 31, v118
	s_and_b64 vcc, exec, s[4:5]
	v_mov_b32_e32 v135, 0
	v_mov_b32_e32 v136, 0
	v_mov_b32_e32 v137, 0
	v_mov_b32_e32 v131, 1.0
	v_mov_b32_e32 v132, 1.0
	v_mov_b32_e32 v133, 1.0
	s_cbranch_vccnz .LBB0_219
	v_lshlrev_b64 v[120:121], 7, v[118:119]
	v_lshl_add_u64 v[120:121], v[154:155], 0, v[120:121]
	global_load_dwordx4 v[130:133], v[120:121], off
	global_load_dwordx4 v[134:137], v[120:121], off offset:64
.LBB0_219:
	s_waitcnt vmcnt(1)
	v_pk_mul_f32 v[138:139], v[106:107], v[130:131]
	v_lshlrev_b64 v[180:181], 8, v[118:119]
	s_waitcnt vmcnt(0)
	v_pk_mul_f32 v[118:119], v[108:109], v[136:137]
	v_pk_mul_f32 v[120:121], v[106:107], v[134:135]
	v_pk_fma_f32 v[138:139], v[110:111], v[134:135], v[138:139]
	v_pk_fma_f32 v[118:119], v[112:113], v[132:133], v[118:119] neg_lo:[0,0,1] neg_hi:[0,0,1]
	v_pk_fma_f32 v[120:121], v[110:111], v[130:131], v[120:121] neg_lo:[0,0,1] neg_hi:[0,0,1]
	v_pk_mul_f32 v[126:127], v[108:109], v[132:133]
	v_cndmask_b32_e64 v141, v107, v139, s[76:77]
	v_cndmask_b32_e64 v140, v106, v138, s[76:77]
	v_lshl_add_u64 v[106:107], s[80:81], 0, v[180:181]
	v_pk_fma_f32 v[126:127], v[112:113], v[136:137], v[126:127]
	v_cndmask_b32_e64 v173, v111, v121, s[76:77]
	v_cndmask_b32_e64 v172, v110, v120, s[76:77]
	v_cndmask_b32_e64 v143, v113, v119, s[76:77]
	v_cndmask_b32_e64 v142, v112, v118, s[76:77]
	v_lshl_add_u64 v[106:107], v[106:107], 0, s[16:17]
	v_cndmask_b32_e64 v139, v109, v127, s[76:77]
	v_cndmask_b32_e64 v138, v108, v126, s[76:77]
	v_lshl_add_u64 v[106:107], v[106:107], 0, v[148:149]
	v_cvt_pk_bf16_f32 v108, v172, v173
	v_cvt_pk_bf16_f32 v109, v142, v143
	v_pk_mul_f32 v[112:113], v[98:99], v[130:131]
	v_cvt_pk_bf16_f32 v110, v140, v141
	v_cvt_pk_bf16_f32 v111, v138, v139
	s_nop 1
	v_permlane16_swap_b32_e32 v108, v110
	v_permlane16_swap_b32_e32 v109, v111
	global_store_dwordx4 v[106:107], v[108:111], off
	s_nop 1
	v_pk_mul_f32 v[106:107], v[100:101], v[136:137]
	v_pk_mul_f32 v[108:109], v[98:99], v[134:135]
	v_pk_fma_f32 v[112:113], v[102:103], v[134:135], v[112:113]
	v_pk_fma_f32 v[106:107], v[104:105], v[132:133], v[106:107] neg_lo:[0,0,1] neg_hi:[0,0,1]
	v_pk_fma_f32 v[108:109], v[102:103], v[130:131], v[108:109] neg_lo:[0,0,1] neg_hi:[0,0,1]
	v_pk_mul_f32 v[110:111], v[100:101], v[132:133]
	v_cndmask_b32_e64 v119, v99, v113, s[76:77]
	v_cndmask_b32_e64 v118, v98, v112, s[76:77]
	v_lshl_add_u64 v[98:99], s[82:83], 0, v[180:181]
	v_pk_fma_f32 v[110:111], v[104:105], v[136:137], v[110:111]
	v_cndmask_b32_e64 v127, v103, v109, s[76:77]
	v_cndmask_b32_e64 v126, v102, v108, s[76:77]
	v_cndmask_b32_e64 v121, v105, v107, s[76:77]
	v_cndmask_b32_e64 v120, v104, v106, s[76:77]
	v_lshl_add_u64 v[98:99], v[98:99], 0, s[16:17]
	v_cndmask_b32_e64 v113, v101, v111, s[76:77]
	v_cndmask_b32_e64 v112, v100, v110, s[76:77]
	v_lshl_add_u64 v[98:99], v[98:99], 0, v[148:149]
	v_cvt_pk_bf16_f32 v100, v126, v127
	v_cvt_pk_bf16_f32 v101, v120, v121
	v_cvt_pk_bf16_f32 v102, v118, v119
	v_cvt_pk_bf16_f32 v103, v112, v113
	s_nop 1
	v_permlane16_swap_b32_e32 v100, v102
	v_permlane16_swap_b32_e32 v101, v103
	global_store_dwordx4 v[98:99], v[100:103], off
	s_nop 1
	v_or_b32_e32 v100, 32, v170
	v_ashrrev_i32_e32 v101, 31, v100
	v_mov_b32_e32 v98, 1.0
	v_mov_b32_e32 v102, 0
	s_and_b64 vcc, exec, s[4:5]
	v_mov_b32_e32 v104, 0
	v_mov_b32_e32 v105, 0
	v_mov_b32_e32 v106, 0
	v_mov_b32_e32 v107, 0
	v_mov_b32_e32 v108, 1.0
	v_mov_b32_e32 v109, 1.0
	v_mov_b32_e32 v110, 1.0
	v_mov_b32_e32 v111, 1.0
	s_cbranch_vccnz .LBB0_221
; __device__ __forceinline__ unsigned cvt_pk_bf16(float lo, float hi) { f32x2_c v = {lo, hi}; bf16x2_c b = __builtin_convertvector(v, bf16x2_c); return __builtin_bit_cast(unsigned, b); }
;     __device__ __forceinline__ void operator()(const f32x4 (&acc)[2][2][4][2], const Unit& u, int wr, int wc, int fr, int fq) const {
;     ...
;                 for (int m = 0; m < 4; ++m) { const int r = row0 + ai * HALF + m * 16, pos = r - b * SEQ;
;                     f32x4 cs = (f32x4){1.f, 1.f, 1.f, 1.f}, sn = (f32x4){0.f, 0.f, 0.f, 0.f};
;                     if (rot) { cs = *(const f32x4*)(rope + (size_t)pos * 32 + 4 * fq); sn = *(const f32x4*)(rope + (size_t)pos * 32 + 16 + 4 * fq); }
; #pragma unroll
;                     for (int bj = 0; bj < 2; ++bj) { const int h8 = (pn & 3) * 2 + bj; f32x4 v0 = acc[ai][bj][m][0], v1 = acc[ai][bj][m][1];
;                         if (rot) { const f32x4 a = v0 * cs - v1 * sn, bb = v1 * cs + v0 * sn; v0 = a; v1 = bb; }
;                         if (sec == 1) { ks[bj][0] += v0; ks[bj][1] += v1; }
;                         bf16_t* dst = QKV + (size_t)sec * SEC_ELEMS + ((size_t)(b * NH8 + h8) * SEQ + pos) * 128 + wc * 32 + 4 * fq;
;                         u32x2 w0, w1; w0.x = cvt_pk_bf16(v0[0], v0[1]); w0.y = cvt_pk_bf16(v0[2], v0[3]); w1.x = cvt_pk_bf16(v1[0], v1[1]); w1.y = cvt_pk_bf16(v1[2], v1[3]);
;                         *(u32x2*)dst = w0; *(u32x2*)(dst + 16) = w1; } }
	v_lshlrev_b64 v[104:105], 7, v[100:101]
	v_lshl_add_u64 v[104:105], v[154:155], 0, v[104:105]
	global_load_dwordx4 v[108:111], v[104:105], off
	s_nop 0
	global_load_dwordx4 v[104:107], v[104:105], off offset:64
.LBB0_221:
	s_waitcnt vmcnt(0)
	v_pk_mul_f32 v[132:133], v[90:91], v[104:105]
	v_lshlrev_b64 v[100:101], 8, v[100:101]
	v_pk_fma_f32 v[136:137], v[94:95], v[108:109], v[132:133] neg_lo:[0,0,1] neg_hi:[0,0,1]
	v_pk_mul_f32 v[132:133], v[90:91], v[108:109]
	v_pk_mul_f32 v[130:131], v[92:93], v[106:107]
	v_pk_fma_f32 v[132:133], v[94:95], v[104:105], v[132:133]
	v_pk_fma_f32 v[134:135], v[96:97], v[110:111], v[130:131] neg_lo:[0,0,1] neg_hi:[0,0,1]
	v_pk_mul_f32 v[130:131], v[92:93], v[110:111]
	v_cndmask_b32_e64 v133, v91, v133, s[76:77]
	v_cndmask_b32_e64 v132, v90, v132, s[76:77]
	v_lshl_add_u64 v[90:91], s[80:81], 0, v[100:101]
	v_pk_fma_f32 v[130:131], v[96:97], v[106:107], v[130:131]
	v_cndmask_b32_e64 v137, v95, v137, s[76:77]
	v_cndmask_b32_e64 v136, v94, v136, s[76:77]
	v_cndmask_b32_e64 v135, v97, v135, s[76:77]
	v_cndmask_b32_e64 v134, v96, v134, s[76:77]
	v_lshl_add_u64 v[90:91], v[90:91], 0, s[16:17]
	v_cndmask_b32_e64 v131, v93, v131, s[76:77]
	v_cndmask_b32_e64 v130, v92, v130, s[76:77]
	v_lshl_add_u64 v[90:91], v[90:91], 0, v[148:149]
	v_cvt_pk_bf16_f32 v92, v136, v137
	v_cvt_pk_bf16_f32 v93, v134, v135
	v_cvt_pk_bf16_f32 v94, v132, v133
	v_cvt_pk_bf16_f32 v95, v130, v131
	s_nop 1
	v_permlane16_swap_b32_e32 v92, v94
	v_permlane16_swap_b32_e32 v93, v95
	global_store_dwordx4 v[90:91], v[92:95], off
	s_nop 1
	v_pk_mul_f32 v[90:91], v[84:85], v[106:107]
	v_pk_mul_f32 v[92:93], v[82:83], v[104:105]
	v_pk_fma_f32 v[94:95], v[88:89], v[110:111], v[90:91] neg_lo:[0,0,1] neg_hi:[0,0,1]
	v_pk_fma_f32 v[92:93], v[86:87], v[108:109], v[92:93] neg_lo:[0,0,1] neg_hi:[0,0,1]
	v_pk_mul_f32 v[90:91], v[84:85], v[110:111]
	v_pk_mul_f32 v[96:97], v[82:83], v[108:109]
	v_pk_fma_f32 v[106:107], v[88:89], v[106:107], v[90:91]
	v_pk_fma_f32 v[90:91], v[86:87], v[104:105], v[96:97]
	v_cndmask_b32_e64 v93, v87, v93, s[76:77]
	v_cndmask_b32_e64 v92, v86, v92, s[76:77]
	v_lshl_add_u64 v[86:87], s[82:83], 0, v[100:101]
	v_cndmask_b32_e64 v91, v83, v91, s[76:77]
	v_cndmask_b32_e64 v90, v82, v90, s[76:77]
	v_cndmask_b32_e64 v83, v85, v107, s[76:77]
	v_cndmask_b32_e64 v82, v84, v106, s[76:77]
	v_cndmask_b32_e64 v85, v89, v95, s[76:77]
	v_cndmask_b32_e64 v84, v88, v94, s[76:77]
	v_lshl_add_u64 v[86:87], v[86:87], 0, s[16:17]
	v_lshl_add_u64 v[86:87], v[86:87], 0, v[148:149]
	v_cvt_pk_bf16_f32 v88, v92, v93
	v_cvt_pk_bf16_f32 v89, v84, v85
	v_cvt_pk_bf16_f32 v94, v90, v91
	v_cvt_pk_bf16_f32 v95, v82, v83
	s_nop 1
	v_permlane16_swap_b32_e32 v88, v94
	v_permlane16_swap_b32_e32 v89, v95
	v_mov_b32_e32 v192, v88
	v_mov_b32_e32 v193, v89
	v_mov_b32_e32 v194, v94
	v_mov_b32_e32 v195, v95
	global_store_dwordx4 v[86:87], v[192:195], off
	v_or_b32_e32 v86, 48, v170
	v_ashrrev_i32_e32 v87, 31, v86
	s_and_b64 vcc, exec, s[4:5]
	v_mov_b32_e32 v103, 0
	v_mov_b32_e32 v104, 0
	v_mov_b32_e32 v105, 0
	v_mov_b32_e32 v99, 1.0
	v_mov_b32_e32 v100, 1.0
	v_mov_b32_e32 v101, 1.0
	s_cbranch_vccnz .LBB0_223
	v_lshlrev_b64 v[88:89], 7, v[86:87]
	v_lshl_add_u64 v[88:89], v[154:155], 0, v[88:89]
	global_load_dwordx4 v[98:101], v[88:89], off
	global_load_dwordx4 v[102:105], v[88:89], off offset:64
.LBB0_223:
	s_waitcnt vmcnt(1)
	v_pk_mul_f32 v[96:97], v[74:75], v[98:99]
	v_lshlrev_b64 v[180:181], 8, v[86:87]
	s_waitcnt vmcnt(0)
	v_pk_mul_f32 v[86:87], v[76:77], v[104:105]
	v_pk_mul_f32 v[88:89], v[74:75], v[102:103]
	v_pk_fma_f32 v[96:97], v[78:79], v[102:103], v[96:97]
	v_pk_fma_f32 v[86:87], v[80:81], v[100:101], v[86:87] neg_lo:[0,0,1] neg_hi:[0,0,1]
	v_pk_fma_f32 v[88:89], v[78:79], v[98:99], v[88:89] neg_lo:[0,0,1] neg_hi:[0,0,1]
	v_pk_mul_f32 v[94:95], v[76:77], v[100:101]
	v_cndmask_b32_e64 v107, v75, v97, s[76:77]
	v_cndmask_b32_e64 v106, v74, v96, s[76:77]
	v_lshl_add_u64 v[74:75], s[80:81], 0, v[180:181]
	v_pk_fma_f32 v[94:95], v[80:81], v[104:105], v[94:95]
	v_cndmask_b32_e64 v111, v79, v89, s[76:77]
	v_cndmask_b32_e64 v110, v78, v88, s[76:77]
	v_cndmask_b32_e64 v109, v81, v87, s[76:77]
	v_cndmask_b32_e64 v108, v80, v86, s[76:77]
	v_lshl_add_u64 v[74:75], v[74:75], 0, s[16:17]
	v_cndmask_b32_e64 v97, v77, v95, s[76:77]
	v_cndmask_b32_e64 v96, v76, v94, s[76:77]
	v_lshl_add_u64 v[74:75], v[74:75], 0, v[148:149]
	v_cvt_pk_bf16_f32 v76, v110, v111
	v_cvt_pk_bf16_f32 v77, v108, v109
	v_pk_mul_f32 v[80:81], v[66:67], v[98:99]
	v_cvt_pk_bf16_f32 v78, v106, v107
	v_cvt_pk_bf16_f32 v79, v96, v97
	s_nop 1
	v_permlane16_swap_b32_e32 v76, v78
	v_permlane16_swap_b32_e32 v77, v79
	global_store_dwordx4 v[74:75], v[76:79], off
	s_nop 1
	v_pk_mul_f32 v[74:75], v[68:69], v[104:105]
	v_pk_mul_f32 v[76:77], v[66:67], v[102:103]
	v_pk_fma_f32 v[80:81], v[70:71], v[102:103], v[80:81]
	v_pk_fma_f32 v[74:75], v[72:73], v[100:101], v[74:75] neg_lo:[0,0,1] neg_hi:[0,0,1]
	v_pk_fma_f32 v[76:77], v[70:71], v[98:99], v[76:77] neg_lo:[0,0,1] neg_hi:[0,0,1]
	v_pk_mul_f32 v[78:79], v[68:69], v[100:101]
	v_cndmask_b32_e64 v87, v67, v81, s[76:77]
	v_cndmask_b32_e64 v86, v66, v80, s[76:77]
	v_lshl_add_u64 v[66:67], s[82:83], 0, v[180:181]
	v_pk_fma_f32 v[78:79], v[72:73], v[104:105], v[78:79]
	v_cndmask_b32_e64 v95, v71, v77, s[76:77]
	v_cndmask_b32_e64 v94, v70, v76, s[76:77]
	v_cndmask_b32_e64 v89, v73, v75, s[76:77]
	v_cndmask_b32_e64 v88, v72, v74, s[76:77]
	v_lshl_add_u64 v[66:67], v[66:67], 0, s[16:17]
	v_cndmask_b32_e64 v81, v69, v79, s[76:77]
	v_cndmask_b32_e64 v80, v68, v78, s[76:77]
	v_lshl_add_u64 v[66:67], v[66:67], 0, v[148:149]
	v_cvt_pk_bf16_f32 v68, v94, v95
	v_cvt_pk_bf16_f32 v69, v88, v89
	v_cvt_pk_bf16_f32 v70, v86, v87
	v_cvt_pk_bf16_f32 v71, v80, v81
	s_nop 1
	v_permlane16_swap_b32_e32 v68, v70
	v_permlane16_swap_b32_e32 v69, v71
	global_store_dwordx4 v[66:67], v[68:71], off
	s_nop 1
	v_add_u32_e32 v68, 0x80, v170
	v_ashrrev_i32_e32 v69, 31, v68
	v_mov_b32_e32 v66, 1.0
	v_mov_b32_e32 v70, 0
	s_and_b64 vcc, exec, s[4:5]
	v_mov_b32_e32 v72, 0
	v_mov_b32_e32 v73, 0
	v_mov_b32_e32 v74, 0
	v_mov_b32_e32 v75, 0
	v_mov_b32_e32 v76, 1.0
	v_mov_b32_e32 v77, 1.0
	v_mov_b32_e32 v78, 1.0
	v_mov_b32_e32 v79, 1.0
	s_cbranch_vccnz .LBB0_225
	v_lshlrev_b64 v[72:73], 7, v[68:69]
	v_lshl_add_u64 v[72:73], v[154:155], 0, v[72:73]
	global_load_dwordx4 v[76:79], v[72:73], off
	s_nop 0
	global_load_dwordx4 v[72:75], v[72:73], off offset:64
; __device__ __forceinline__ unsigned cvt_pk_bf16(float lo, float hi) { f32x2_c v = {lo, hi}; bf16x2_c b = __builtin_convertvector(v, bf16x2_c); return __builtin_bit_cast(unsigned, b); }
;     __device__ __forceinline__ void operator()(const f32x4 (&acc)[2][2][4][2], const Unit& u, int wr, int wc, int fr, int fq) const {
;     ...
;                 for (int m = 0; m < 4; ++m) { const int r = row0 + ai * HALF + m * 16, pos = r - b * SEQ;
;                     f32x4 cs = (f32x4){1.f, 1.f, 1.f, 1.f}, sn = (f32x4){0.f, 0.f, 0.f, 0.f};
;                     if (rot) { cs = *(const f32x4*)(rope + (size_t)pos * 32 + 4 * fq); sn = *(const f32x4*)(rope + (size_t)pos * 32 + 16 + 4 * fq); }
; #pragma unroll
;                     for (int bj = 0; bj < 2; ++bj) { const int h8 = (pn & 3) * 2 + bj; f32x4 v0 = acc[ai][bj][m][0], v1 = acc[ai][bj][m][1];
;                         if (rot) { const f32x4 a = v0 * cs - v1 * sn, bb = v1 * cs + v0 * sn; v0 = a; v1 = bb; }
;                         if (sec == 1) { ks[bj][0] += v0; ks[bj][1] += v1; }
;                         bf16_t* dst = QKV + (size_t)sec * SEC_ELEMS + ((size_t)(b * NH8 + h8) * SEQ + pos) * 128 + wc * 32 + 4 * fq;
;                         u32x2 w0, w1; w0.x = cvt_pk_bf16(v0[0], v0[1]); w0.y = cvt_pk_bf16(v0[2], v0[3]); w1.x = cvt_pk_bf16(v1[0], v1[1]); w1.y = cvt_pk_bf16(v1[2], v1[3]);
;                         *(u32x2*)dst = w0; *(u32x2*)(dst + 16) = w1; } }
.LBB0_225:
	s_waitcnt vmcnt(0)
	v_pk_mul_f32 v[100:101], v[58:59], v[72:73]
	v_lshlrev_b64 v[68:69], 8, v[68:69]
	v_pk_fma_f32 v[104:105], v[62:63], v[76:77], v[100:101] neg_lo:[0,0,1] neg_hi:[0,0,1]
	v_pk_mul_f32 v[100:101], v[58:59], v[76:77]
	v_pk_mul_f32 v[98:99], v[60:61], v[74:75]
	v_pk_fma_f32 v[100:101], v[62:63], v[72:73], v[100:101]
	v_pk_fma_f32 v[102:103], v[64:65], v[78:79], v[98:99] neg_lo:[0,0,1] neg_hi:[0,0,1]
	v_pk_mul_f32 v[98:99], v[60:61], v[78:79]
	v_cndmask_b32_e64 v101, v59, v101, s[76:77]
	v_cndmask_b32_e64 v100, v58, v100, s[76:77]
	v_lshl_add_u64 v[58:59], s[80:81], 0, v[68:69]
	v_pk_fma_f32 v[98:99], v[64:65], v[74:75], v[98:99]
	v_cndmask_b32_e64 v105, v63, v105, s[76:77]
	v_cndmask_b32_e64 v104, v62, v104, s[76:77]
	v_cndmask_b32_e64 v103, v65, v103, s[76:77]
	v_cndmask_b32_e64 v102, v64, v102, s[76:77]
	v_lshl_add_u64 v[58:59], v[58:59], 0, s[16:17]
	v_cndmask_b32_e64 v99, v61, v99, s[76:77]
	v_cndmask_b32_e64 v98, v60, v98, s[76:77]
	v_lshl_add_u64 v[58:59], v[58:59], 0, v[148:149]
	v_cvt_pk_bf16_f32 v60, v104, v105
	v_cvt_pk_bf16_f32 v61, v102, v103
	v_cvt_pk_bf16_f32 v62, v100, v101
	v_cvt_pk_bf16_f32 v63, v98, v99
	s_nop 1
	v_permlane16_swap_b32_e32 v60, v62
	v_permlane16_swap_b32_e32 v61, v63
	global_store_dwordx4 v[58:59], v[60:63], off
	s_nop 1
	v_pk_mul_f32 v[58:59], v[52:53], v[74:75]
	v_pk_mul_f32 v[60:61], v[50:51], v[72:73]
	v_pk_fma_f32 v[62:63], v[56:57], v[78:79], v[58:59] neg_lo:[0,0,1] neg_hi:[0,0,1]
	v_pk_fma_f32 v[60:61], v[54:55], v[76:77], v[60:61] neg_lo:[0,0,1] neg_hi:[0,0,1]
	v_pk_mul_f32 v[58:59], v[52:53], v[78:79]
	v_pk_mul_f32 v[64:65], v[50:51], v[76:77]
	v_pk_fma_f32 v[74:75], v[56:57], v[74:75], v[58:59]
	v_pk_fma_f32 v[58:59], v[54:55], v[72:73], v[64:65]
	v_cndmask_b32_e64 v61, v55, v61, s[76:77]
	v_cndmask_b32_e64 v60, v54, v60, s[76:77]
	v_lshl_add_u64 v[54:55], s[82:83], 0, v[68:69]
	v_cndmask_b32_e64 v59, v51, v59, s[76:77]
	v_cndmask_b32_e64 v58, v50, v58, s[76:77]
	v_cndmask_b32_e64 v51, v53, v75, s[76:77]
	v_cndmask_b32_e64 v50, v52, v74, s[76:77]
	v_cndmask_b32_e64 v53, v57, v63, s[76:77]
	v_cndmask_b32_e64 v52, v56, v62, s[76:77]
	v_lshl_add_u64 v[54:55], v[54:55], 0, s[16:17]
	v_lshl_add_u64 v[54:55], v[54:55], 0, v[148:149]
	v_cvt_pk_bf16_f32 v56, v60, v61
	v_cvt_pk_bf16_f32 v57, v52, v53
	v_cvt_pk_bf16_f32 v62, v58, v59
	v_cvt_pk_bf16_f32 v63, v50, v51
	s_nop 1
	v_permlane16_swap_b32_e32 v56, v62
	v_permlane16_swap_b32_e32 v57, v63
	v_mov_b32_e32 v188, v56
	v_mov_b32_e32 v189, v57
	v_mov_b32_e32 v190, v62
	v_mov_b32_e32 v191, v63
	global_store_dwordx4 v[54:55], v[188:191], off
	v_add_u32_e32 v54, 0x90, v170
	v_ashrrev_i32_e32 v55, 31, v54
	s_and_b64 vcc, exec, s[4:5]
	v_mov_b32_e32 v71, 0
	v_mov_b32_e32 v72, 0
	v_mov_b32_e32 v73, 0
	v_mov_b32_e32 v67, 1.0
	v_mov_b32_e32 v68, 1.0
	v_mov_b32_e32 v69, 1.0
	s_cbranch_vccnz .LBB0_227
	v_lshlrev_b64 v[56:57], 7, v[54:55]
	v_lshl_add_u64 v[56:57], v[154:155], 0, v[56:57]
	global_load_dwordx4 v[66:69], v[56:57], off
	global_load_dwordx4 v[70:73], v[56:57], off offset:64
.LBB0_227:
	s_waitcnt vmcnt(1)
	v_pk_mul_f32 v[64:65], v[42:43], v[66:67]
	v_lshlrev_b64 v[180:181], 8, v[54:55]
	s_waitcnt vmcnt(0)
	v_pk_mul_f32 v[54:55], v[44:45], v[72:73]
	v_pk_mul_f32 v[56:57], v[42:43], v[70:71]
	v_pk_fma_f32 v[64:65], v[46:47], v[70:71], v[64:65]
	v_pk_fma_f32 v[54:55], v[48:49], v[68:69], v[54:55] neg_lo:[0,0,1] neg_hi:[0,0,1]
	v_pk_fma_f32 v[56:57], v[46:47], v[66:67], v[56:57] neg_lo:[0,0,1] neg_hi:[0,0,1]
	v_pk_mul_f32 v[62:63], v[44:45], v[68:69]
	v_cndmask_b32_e64 v75, v43, v65, s[76:77]
	v_cndmask_b32_e64 v74, v42, v64, s[76:77]
	v_lshl_add_u64 v[42:43], s[80:81], 0, v[180:181]
	v_pk_fma_f32 v[62:63], v[48:49], v[72:73], v[62:63]
	v_cndmask_b32_e64 v79, v47, v57, s[76:77]
	v_cndmask_b32_e64 v78, v46, v56, s[76:77]
	v_cndmask_b32_e64 v77, v49, v55, s[76:77]
	v_cndmask_b32_e64 v76, v48, v54, s[76:77]
	v_lshl_add_u64 v[42:43], v[42:43], 0, s[16:17]
	v_cndmask_b32_e64 v65, v45, v63, s[76:77]
	v_cndmask_b32_e64 v64, v44, v62, s[76:77]
	v_lshl_add_u64 v[42:43], v[42:43], 0, v[148:149]
	v_cvt_pk_bf16_f32 v44, v78, v79
	v_cvt_pk_bf16_f32 v45, v76, v77
	v_pk_mul_f32 v[48:49], v[34:35], v[66:67]
	v_cvt_pk_bf16_f32 v46, v74, v75
	v_cvt_pk_bf16_f32 v47, v64, v65
	s_nop 1
	v_permlane16_swap_b32_e32 v44, v46
	v_permlane16_swap_b32_e32 v45, v47
	global_store_dwordx4 v[42:43], v[44:47], off
	s_nop 1
	v_pk_mul_f32 v[42:43], v[36:37], v[72:73]
	v_pk_mul_f32 v[44:45], v[34:35], v[70:71]
	v_pk_fma_f32 v[48:49], v[38:39], v[70:71], v[48:49]
	v_pk_fma_f32 v[42:43], v[40:41], v[68:69], v[42:43] neg_lo:[0,0,1] neg_hi:[0,0,1]
	v_pk_fma_f32 v[44:45], v[38:39], v[66:67], v[44:45] neg_lo:[0,0,1] neg_hi:[0,0,1]
	v_pk_mul_f32 v[46:47], v[36:37], v[68:69]
	v_cndmask_b32_e64 v55, v35, v49, s[76:77]
	v_cndmask_b32_e64 v54, v34, v48, s[76:77]
	v_lshl_add_u64 v[34:35], s[82:83], 0, v[180:181]
	v_pk_fma_f32 v[46:47], v[40:41], v[72:73], v[46:47]
	v_cndmask_b32_e64 v63, v39, v45, s[76:77]
	v_cndmask_b32_e64 v62, v38, v44, s[76:77]
	v_cndmask_b32_e64 v57, v41, v43, s[76:77]
	v_cndmask_b32_e64 v56, v40, v42, s[76:77]
	v_lshl_add_u64 v[34:35], v[34:35], 0, s[16:17]
	v_cndmask_b32_e64 v49, v37, v47, s[76:77]
	v_cndmask_b32_e64 v48, v36, v46, s[76:77]
	v_lshl_add_u64 v[34:35], v[34:35], 0, v[148:149]
	v_cvt_pk_bf16_f32 v36, v62, v63
	v_cvt_pk_bf16_f32 v37, v56, v57
	v_cvt_pk_bf16_f32 v38, v54, v55
	v_cvt_pk_bf16_f32 v39, v48, v49
	s_nop 1
	v_permlane16_swap_b32_e32 v36, v38
	v_permlane16_swap_b32_e32 v37, v39
	global_store_dwordx4 v[34:35], v[36:39], off
	s_nop 1
	v_add_u32_e32 v36, 0xa0, v170
	v_ashrrev_i32_e32 v37, 31, v36
	v_mov_b32_e32 v34, 1.0
	v_mov_b32_e32 v38, 0
	s_and_b64 vcc, exec, s[4:5]
	v_mov_b32_e32 v40, 0
	v_mov_b32_e32 v41, 0
	v_mov_b32_e32 v42, 0
	v_mov_b32_e32 v43, 0
	v_mov_b32_e32 v44, 1.0
	v_mov_b32_e32 v45, 1.0
	v_mov_b32_e32 v46, 1.0
	v_mov_b32_e32 v47, 1.0
	s_cbranch_vccnz .LBB0_229
	v_lshlrev_b64 v[40:41], 7, v[36:37]
	v_lshl_add_u64 v[40:41], v[154:155], 0, v[40:41]
	global_load_dwordx4 v[44:47], v[40:41], off
	s_nop 0
	global_load_dwordx4 v[40:43], v[40:41], off offset:64
; __device__ __forceinline__ unsigned cvt_pk_bf16(float lo, float hi) { f32x2_c v = {lo, hi}; bf16x2_c b = __builtin_convertvector(v, bf16x2_c); return __builtin_bit_cast(unsigned, b); }
;     __device__ __forceinline__ void operator()(const f32x4 (&acc)[2][2][4][2], const Unit& u, int wr, int wc, int fr, int fq) const {
;     ...
;                 for (int m = 0; m < 4; ++m) { const int r = row0 + ai * HALF + m * 16, pos = r - b * SEQ;
;                     f32x4 cs = (f32x4){1.f, 1.f, 1.f, 1.f}, sn = (f32x4){0.f, 0.f, 0.f, 0.f};
;                     if (rot) { cs = *(const f32x4*)(rope + (size_t)pos * 32 + 4 * fq); sn = *(const f32x4*)(rope + (size_t)pos * 32 + 16 + 4 * fq); }
; #pragma unroll
;                     for (int bj = 0; bj < 2; ++bj) { const int h8 = (pn & 3) * 2 + bj; f32x4 v0 = acc[ai][bj][m][0], v1 = acc[ai][bj][m][1];
;                         if (rot) { const f32x4 a = v0 * cs - v1 * sn, bb = v1 * cs + v0 * sn; v0 = a; v1 = bb; }
;                         if (sec == 1) { ks[bj][0] += v0; ks[bj][1] += v1; }
;                         bf16_t* dst = QKV + (size_t)sec * SEC_ELEMS + ((size_t)(b * NH8 + h8) * SEQ + pos) * 128 + wc * 32 + 4 * fq;
;                         u32x2 w0, w1; w0.x = cvt_pk_bf16(v0[0], v0[1]); w0.y = cvt_pk_bf16(v0[2], v0[3]); w1.x = cvt_pk_bf16(v1[0], v1[1]); w1.y = cvt_pk_bf16(v1[2], v1[3]);
;                         *(u32x2*)dst = w0; *(u32x2*)(dst + 16) = w1; } }
.LBB0_229:
	s_waitcnt vmcnt(0)
	v_pk_mul_f32 v[66:67], v[28:29], v[42:43]
	v_pk_mul_f32 v[72:73], v[26:27], v[44:45]
	v_pk_fma_f32 v[70:71], v[32:33], v[46:47], v[66:67] neg_lo:[0,0,1] neg_hi:[0,0,1]
	v_pk_mul_f32 v[66:67], v[28:29], v[46:47]
	v_lshlrev_b64 v[36:37], 8, v[36:37]
	v_pk_mul_f32 v[68:69], v[26:27], v[40:41]
	v_pk_fma_f32 v[180:181], v[32:33], v[42:43], v[66:67]
	v_pk_fma_f32 v[66:67], v[30:31], v[40:41], v[72:73]
	v_pk_fma_f32 v[68:69], v[30:31], v[44:45], v[68:69] neg_lo:[0,0,1] neg_hi:[0,0,1]
	v_cndmask_b32_e64 v67, v27, v67, s[76:77]
	v_cndmask_b32_e64 v66, v26, v66, s[76:77]
	v_lshl_add_u64 v[26:27], s[80:81], 0, v[36:37]
	v_cndmask_b32_e64 v69, v31, v69, s[76:77]
	v_cndmask_b32_e64 v68, v30, v68, s[76:77]
	v_cndmask_b32_e64 v31, v33, v71, s[76:77]
	v_cndmask_b32_e64 v30, v32, v70, s[76:77]
	v_lshl_add_u64 v[26:27], v[26:27], 0, s[16:17]
	v_cndmask_b32_e64 v29, v29, v181, s[76:77]
	v_cndmask_b32_e64 v28, v28, v180, s[76:77]
	v_lshl_add_u64 v[26:27], v[26:27], 0, v[148:149]
	v_cvt_pk_bf16_f32 v32, v68, v69
	v_cvt_pk_bf16_f32 v33, v30, v31
	v_cvt_pk_bf16_f32 v70, v66, v67
	v_cvt_pk_bf16_f32 v71, v28, v29
	s_nop 1
	v_permlane16_swap_b32_e32 v32, v70
	v_permlane16_swap_b32_e32 v33, v71
	v_mov_b32_e32 v192, v32
	v_mov_b32_e32 v193, v33
	v_mov_b32_e32 v194, v70
	v_mov_b32_e32 v195, v71
	global_store_dwordx4 v[26:27], v[192:195], off
	v_pk_mul_f32 v[26:27], v[20:21], v[42:43]
	v_pk_mul_f32 v[32:33], v[18:19], v[40:41]
	v_pk_fma_f32 v[70:71], v[24:25], v[46:47], v[26:27] neg_lo:[0,0,1] neg_hi:[0,0,1]
	v_pk_fma_f32 v[32:33], v[22:23], v[44:45], v[32:33] neg_lo:[0,0,1] neg_hi:[0,0,1]
	v_pk_mul_f32 v[26:27], v[20:21], v[46:47]
	v_pk_mul_f32 v[44:45], v[18:19], v[44:45]
	v_pk_fma_f32 v[42:43], v[24:25], v[42:43], v[26:27]
	v_pk_fma_f32 v[26:27], v[22:23], v[40:41], v[44:45]
	v_cndmask_b32_e64 v23, v23, v33, s[76:77]
	v_cndmask_b32_e64 v27, v19, v27, s[76:77]
	v_cndmask_b32_e64 v26, v18, v26, s[76:77]
	v_cndmask_b32_e64 v19, v21, v43, s[76:77]
	v_cndmask_b32_e64 v18, v20, v42, s[76:77]
	v_cndmask_b32_e64 v21, v25, v71, s[76:77]
	v_cndmask_b32_e64 v20, v24, v70, s[76:77]
	v_lshl_add_u64 v[24:25], s[82:83], 0, v[36:37]
	v_cndmask_b32_e64 v22, v22, v32, s[76:77]
	v_lshl_add_u64 v[24:25], v[24:25], 0, s[16:17]
	v_lshl_add_u64 v[24:25], v[24:25], 0, v[148:149]
	v_cvt_pk_bf16_f32 v32, v22, v23
	v_cvt_pk_bf16_f32 v33, v20, v21
	v_cvt_pk_bf16_f32 v36, v26, v27
	v_cvt_pk_bf16_f32 v37, v18, v19
	s_nop 1
	v_permlane16_swap_b32_e32 v32, v36
	v_permlane16_swap_b32_e32 v33, v37
	v_mov_b32_e32 v188, v32
	v_mov_b32_e32 v189, v33
	v_mov_b32_e32 v190, v36
	v_mov_b32_e32 v191, v37
	global_store_dwordx4 v[24:25], v[188:191], off
	v_add_u32_e32 v24, 0xb0, v170
	v_ashrrev_i32_e32 v25, 31, v24
	s_and_b64 vcc, exec, s[4:5]
	v_mov_b32_e32 v39, 0
	v_mov_b32_e32 v40, 0
	v_mov_b32_e32 v41, 0
	v_mov_b32_e32 v35, 1.0
	v_mov_b32_e32 v36, 1.0
	v_mov_b32_e32 v37, 1.0
	s_cbranch_vccnz .LBB0_231
	v_lshlrev_b64 v[32:33], 7, v[24:25]
	v_lshl_add_u64 v[32:33], v[154:155], 0, v[32:33]
	global_load_dwordx4 v[34:37], v[32:33], off
	global_load_dwordx4 v[38:41], v[32:33], off offset:64
; __device__ __forceinline__ unsigned cvt_pk_bf16(float lo, float hi) { f32x2_c v = {lo, hi}; bf16x2_c b = __builtin_convertvector(v, bf16x2_c); return __builtin_bit_cast(unsigned, b); }
;     __device__ __forceinline__ void operator()(const f32x4 (&acc)[2][2][4][2], const Unit& u, int wr, int wc, int fr, int fq) const {
;     ...
;                 for (int m = 0; m < 4; ++m) { const int r = row0 + ai * HALF + m * 16, pos = r - b * SEQ;
;                     f32x4 cs = (f32x4){1.f, 1.f, 1.f, 1.f}, sn = (f32x4){0.f, 0.f, 0.f, 0.f};
;                     if (rot) { cs = *(const f32x4*)(rope + (size_t)pos * 32 + 4 * fq); sn = *(const f32x4*)(rope + (size_t)pos * 32 + 16 + 4 * fq); }
; #pragma unroll
;                     for (int bj = 0; bj < 2; ++bj) { const int h8 = (pn & 3) * 2 + bj; f32x4 v0 = acc[ai][bj][m][0], v1 = acc[ai][bj][m][1];
;                         if (rot) { const f32x4 a = v0 * cs - v1 * sn, bb = v1 * cs + v0 * sn; v0 = a; v1 = bb; }
;                         if (sec == 1) { ks[bj][0] += v0; ks[bj][1] += v1; }
;                         bf16_t* dst = QKV + (size_t)sec * SEC_ELEMS + ((size_t)(b * NH8 + h8) * SEQ + pos) * 128 + wc * 32 + 4 * fq;
;                         u32x2 w0, w1; w0.x = cvt_pk_bf16(v0[0], v0[1]); w0.y = cvt_pk_bf16(v0[2], v0[3]); w1.x = cvt_pk_bf16(v1[0], v1[1]); w1.y = cvt_pk_bf16(v1[2], v1[3]);
;                         *(u32x2*)dst = w0; *(u32x2*)(dst + 16) = w1; } }
;             if (sec == 1) {
;                 const int blk = u.pm - b * (SEQ / 256);
; #pragma unroll
;                 for (int bj = 0; bj < 2; ++bj)
; #pragma unroll
;                     for (int n = 0; n < 2; ++n)
; #pragma unroll
;                         for (int e = 0; e < 4; ++e) { float v = ks[bj][n][e]; v += __shfl_xor(v, 1); v += __shfl_xor(v, 2); v += __shfl_xor(v, 4); v += __shfl_xor(v, 8);
;                             if (fr == 0) atomicAdd(km + ((size_t)((b * NH8 + (pn & 3) * 2 + bj) * 64 + blk)) * 128 + wc * 32 + n * 16 + 4 * fq + e, v * (1.0f / 256.0f)); }
.LBB0_231:
	v_lshlrev_b64 v[42:43], 8, v[24:25]
	s_waitcnt vmcnt(0)
	v_pk_mul_f32 v[24:25], v[12:13], v[40:41]
	v_pk_mul_f32 v[46:47], v[10:11], v[34:35]
	v_pk_fma_f32 v[44:45], v[16:17], v[36:37], v[24:25] neg_lo:[0,0,1] neg_hi:[0,0,1]
	v_pk_mul_f32 v[24:25], v[12:13], v[36:37]
	v_pk_mul_f32 v[32:33], v[10:11], v[38:39]
	v_pk_fma_f32 v[70:71], v[16:17], v[40:41], v[24:25]
	v_pk_fma_f32 v[24:25], v[14:15], v[38:39], v[46:47]
	v_pk_fma_f32 v[32:33], v[14:15], v[34:35], v[32:33] neg_lo:[0,0,1] neg_hi:[0,0,1]
	v_cndmask_b32_e64 v25, v11, v25, s[76:77]
	v_cndmask_b32_e64 v24, v10, v24, s[76:77]
	v_lshl_add_u64 v[10:11], s[80:81], 0, v[42:43]
	v_cndmask_b32_e64 v33, v15, v33, s[76:77]
	v_cndmask_b32_e64 v32, v14, v32, s[76:77]
	v_cndmask_b32_e64 v15, v17, v45, s[76:77]
	v_cndmask_b32_e64 v14, v16, v44, s[76:77]
	v_lshl_add_u64 v[10:11], v[10:11], 0, s[16:17]
	v_cndmask_b32_e64 v13, v13, v71, s[76:77]
	v_cndmask_b32_e64 v12, v12, v70, s[76:77]
	v_lshl_add_u64 v[10:11], v[10:11], 0, v[148:149]
	v_cvt_pk_bf16_f32 v16, v32, v33
	v_cvt_pk_bf16_f32 v17, v14, v15
	v_cvt_pk_bf16_f32 v44, v24, v25
	v_cvt_pk_bf16_f32 v45, v12, v13
	s_nop 1
	v_permlane16_swap_b32_e32 v16, v44
	v_permlane16_swap_b32_e32 v17, v45
	v_mov_b32_e32 v192, v16
	v_mov_b32_e32 v193, v17
	v_mov_b32_e32 v194, v44
	v_mov_b32_e32 v195, v45
	global_store_dwordx4 v[10:11], v[192:195], off
	v_pk_mul_f32 v[10:11], v[4:5], v[40:41]
	v_pk_mul_f32 v[16:17], v[2:3], v[38:39]
	v_pk_fma_f32 v[44:45], v[8:9], v[36:37], v[10:11] neg_lo:[0,0,1] neg_hi:[0,0,1]
	v_pk_fma_f32 v[16:17], v[6:7], v[34:35], v[16:17] neg_lo:[0,0,1] neg_hi:[0,0,1]
	v_pk_mul_f32 v[10:11], v[4:5], v[36:37]
	v_pk_mul_f32 v[34:35], v[2:3], v[34:35]
	v_pk_fma_f32 v[36:37], v[8:9], v[40:41], v[10:11]
	v_pk_fma_f32 v[10:11], v[6:7], v[38:39], v[34:35]
	s_cmp_eq_u32 s78, 1
	v_cndmask_b32_e64 v11, v3, v11, s[76:77]
	v_cndmask_b32_e64 v10, v2, v10, s[76:77]
	v_cndmask_b32_e64 v3, v5, v37, s[76:77]
	v_cndmask_b32_e64 v2, v4, v36, s[76:77]
	v_cndmask_b32_e64 v5, v9, v45, s[76:77]
	v_cndmask_b32_e64 v4, v8, v44, s[76:77]
	v_lshl_add_u64 v[8:9], s[82:83], 0, v[42:43]
	v_cndmask_b32_e64 v7, v7, v17, s[76:77]
	v_cndmask_b32_e64 v6, v6, v16, s[76:77]
	v_lshl_add_u64 v[8:9], v[8:9], 0, s[16:17]
	s_cselect_b64 vcc, -1, 0
	s_cmp_lg_u32 s78, 1
	v_lshl_add_u64 v[8:9], v[8:9], 0, v[148:149]
	v_cvt_pk_bf16_f32 v16, v6, v7
	v_cvt_pk_bf16_f32 v17, v4, v5
	v_cvt_pk_bf16_f32 v34, v10, v11
	v_cvt_pk_bf16_f32 v35, v2, v3
	s_nop 1
	v_permlane16_swap_b32_e32 v16, v34
	v_permlane16_swap_b32_e32 v17, v35
	v_mov_b32_e32 v188, v16
	v_mov_b32_e32 v189, v17
	v_mov_b32_e32 v190, v34
	v_mov_b32_e32 v191, v35
	global_store_dwordx4 v[8:9], v[188:191], off
	s_cbranch_scc1 .LBB0_265
	v_pk_add_f32 v[8:9], v[168:169], 0 op_sel_hi:[1,0]
	v_and_b32_e32 v17, 64, v179
	v_pk_add_f32 v[8:9], v[8:9], v[172:173]
	s_lshl_b32 s4, s14, 6
	v_pk_add_f32 v[8:9], v[8:9], v[136:137]
	v_xor_b32_e32 v16, 1, v179
	v_pk_add_f32 v[8:9], v[8:9], v[110:111]
	s_sub_i32 s14, s70, s4
	v_pk_add_f32 v[8:9], v[8:9], v[104:105]
	v_xor_b32_e32 v35, 8, v179
	v_pk_add_f32 v[8:9], v[8:9], v[78:79]
	s_nop 0
	v_pk_add_f32 v[8:9], v[8:9], v[68:69]
	s_nop 0
	v_pk_add_f32 v[8:9], v[8:9], v[32:33]
	v_add_u32_e32 v33, 64, v17
	v_cmp_lt_i32_e64 s[4:5], v16, v33
	v_cndmask_b32_e32 v8, 0, v8, vcc
	v_xor_b32_e32 v17, 2, v179
	v_cndmask_b32_e64 v16, v179, v16, s[4:5]
	v_lshlrev_b32_e32 v16, 2, v16
	ds_bpermute_b32 v32, v16, v8
	v_cmp_lt_i32_e64 s[4:5], v17, v33
	s_waitcnt lgkmcnt(0)
	v_add_f32_e32 v8, v8, v32
	v_cndmask_b32_e64 v17, v179, v17, s[4:5]
	v_lshlrev_b32_e32 v17, 2, v17
	ds_bpermute_b32 v34, v17, v8
	v_xor_b32_e32 v32, 4, v179
	v_cmp_lt_i32_e64 s[4:5], v32, v33
	s_waitcnt lgkmcnt(0)
	v_add_f32_e32 v8, v8, v34
	v_cndmask_b32_e64 v32, v179, v32, s[4:5]
	v_lshlrev_b32_e32 v32, 2, v32
	ds_bpermute_b32 v34, v32, v8
	v_cmp_lt_i32_e64 s[4:5], v35, v33
	s_waitcnt lgkmcnt(0)
	v_add_f32_e32 v8, v8, v34
	v_cndmask_b32_e64 v33, v179, v35, s[4:5]
	v_lshlrev_b32_e32 v33, 2, v33
	ds_bpermute_b32 v34, v33, v8
	s_lshl_b32 s4, s74, 6
	s_add_i32 s4, s4, s14
	s_ashr_i32 s5, s4, 31
	s_lshl_b64 s[4:5], s[4:5], 9
	s_and_saveexec_b64 s[52:53], s[0:1]
	s_cbranch_execz .LBB0_234
	s_waitcnt lgkmcnt(0)
	v_add_f32_e32 v8, v8, v34
	v_mul_f32_e32 v8, 0x3b800000, v8
	v_lshl_add_u64 v[34:35], v[152:153], 0, s[4:5]
	global_atomic_add_f32 v[34:35], v8, off
